# grid barrier: two release polls kept in flight per poller (poll result lands in an otherwise unused VGPR), post-release queue-drain waits dropped
# baseline (speedup 1.0000x reference)
; __device__ __forceinline__ unsigned xb_ld(unsigned* p)              { return __hip_atomic_load(p, __ATOMIC_RELAXED, __HIP_MEMORY_SCOPE_AGENT); }
; __device__ __forceinline__ unsigned xb_add(unsigned* p, unsigned v) { return __hip_atomic_fetch_add(p, v, __ATOMIC_RELAXED, __HIP_MEMORY_SCOPE_AGENT); }
; #define XB_SPIN(cond, bar) do { unsigned _sp = 0; while (cond) { __builtin_amdgcn_s_sleep(1); \
;     if ((++_sp & 255u) == 0u) { if (xb_ld(&(bar)[XB_TMO])) break; if (_sp > XB_SPIN_CAP) { atomicAdd(&(bar)[XB_TMO], 1u); break; } } } } while (0)
; __device__ __forceinline__ void xcd_barrier(const XcdBarrier& b, bool leader) {
;     ...
;         const unsigned old = xb_add(&bar[XB_XSUB(b.x)], 1u);
;         const unsigned gen = old / nloc;
;         if (old + 1u == (gen + 1u) * nloc) {
;             __builtin_amdgcn_fence(__ATOMIC_RELEASE, "agent");
;             asm volatile("s_waitcnt vmcnt(0)" ::: "memory");
;             const unsigned og = xb_add(&bar[XB_TOP], 1u);
;             const unsigned tg = og / nx;
;             if (og + 1u == (tg + 1u) * nx) xb_add(&bar[XB_TOPGEN], 1u);
;             else XB_SPIN(xb_ld(&bar[XB_TOPGEN]) == tg, bar);
;             __builtin_amdgcn_fence(__ATOMIC_ACQUIRE, "agent");
;             xb_add(&bar[XB_XGEN(b.x)], 1u);
;             asm volatile("s_waitcnt vmcnt(0)" ::: "memory");
;         } else {
;             XB_SPIN(xb_ld(&bar[XB_XGEN(b.x)]) == gen, bar);
.LBB0_144:
	s_or_b64 exec, exec, s[10:11]
	v_cvt_f32_u32_e32 v4, v2
	s_waitcnt vmcnt(0)
	v_readfirstlane_b32 s8, v3
	v_sub_u32_e32 v3, 0, v2
	v_rcp_iflag_f32_e32 v4, v4
	v_add_u32_e32 v5, s8, v1
	v_mul_f32_e32 v4, 0x4f7ffffe, v4
	v_cvt_u32_f32_e32 v4, v4
	v_mul_lo_u32 v1, v3, v4
	v_mul_hi_u32 v1, v4, v1
	v_add_u32_e32 v1, v4, v1
	v_mul_hi_u32 v1, v5, v1
	v_mul_lo_u32 v3, v1, v2
	v_sub_u32_e32 v3, v5, v3
	v_add_u32_e32 v4, 1, v1
	v_cmp_ge_u32_e32 vcc, v3, v2
	s_nop 1
	v_cndmask_b32_e32 v1, v1, v4, vcc
	v_sub_u32_e32 v4, v3, v2
	v_cndmask_b32_e32 v3, v3, v4, vcc
	v_add_u32_e32 v4, 1, v1
	v_cmp_ge_u32_e32 vcc, v3, v2
	v_add_u32_e32 v3, 1, v5
	s_nop 0
	v_cndmask_b32_e32 v1, v1, v4, vcc
	v_mul_lo_u32 v4, v2, v1
	v_add_u32_e32 v2, v4, v2
	v_cmp_ne_u32_e32 vcc, v3, v2
	s_and_saveexec_b64 s[8:9], vcc
	s_xor_b64 s[8:9], exec, s[8:9]
	s_cbranch_execz .LBB0_158
	buffer_inv sc1
	s_waitcnt lgkmcnt(0)
	v_add_u32_e32 v1, 1, v1
	v_mul_lo_u32 v1, v1, v0
	v_mov_b32_e32 v0, 0x3000
	global_load_dword v0, v0, s[76:77] offset:1024 sc1
	s_add_u32 s14, s76, 0x3400
	s_addc_u32 s15, s77, 0
	s_waitcnt vmcnt(0)
	v_cmp_lt_u32_e32 vcc, v0, v1
	s_and_saveexec_b64 s[10:11], vcc
	s_cbranch_execz .LBB0_157
	s_mov_b32 s13, 1
	s_mov_b64 s[16:17], 0
	v_mov_b32_e32 v239, v0
	v_mov_b32_e32 v0, 0
	s_branch .LBB0_148

; __device__ __forceinline__ unsigned xb_ld(unsigned* p)              { return __hip_atomic_load(p, __ATOMIC_RELAXED, __HIP_MEMORY_SCOPE_AGENT); }
; #define XB_SPIN(cond, bar) do { unsigned _sp = 0; while (cond) { __builtin_amdgcn_s_sleep(1); \
;     if ((++_sp & 255u) == 0u) { if (xb_ld(&(bar)[XB_TMO])) break; if (_sp > XB_SPIN_CAP) { atomicAdd(&(bar)[XB_TMO], 1u); break; } } } } while (0)
; __device__ __forceinline__ void xcd_barrier(const XcdBarrier& b, bool leader) {
;     ...
;         } else {
;             XB_SPIN(xb_ld(&bar[XB_XGEN(b.x)]) == gen, bar);
.LBB0_152:
	global_load_dword v239, v0, s[14:15] sc1
	s_add_i32 s13, s13, 1
	s_mov_b64 s[22:23], -1
	s_waitcnt vmcnt(1)
	v_cmp_ge_u32_e32 vcc, v239, v1
	s_orn2_b64 s[20:21], vcc, exec
	s_branch .LBB0_147

; __device__ __forceinline__ unsigned xb_ld(unsigned* p)              { return __hip_atomic_load(p, __ATOMIC_RELAXED, __HIP_MEMORY_SCOPE_AGENT); }
; __device__ __forceinline__ unsigned xb_add(unsigned* p, unsigned v) { return __hip_atomic_fetch_add(p, v, __ATOMIC_RELAXED, __HIP_MEMORY_SCOPE_AGENT); }
; #define XB_SPIN(cond, bar) do { unsigned _sp = 0; while (cond) { __builtin_amdgcn_s_sleep(1); \
;     if ((++_sp & 255u) == 0u) { if (xb_ld(&(bar)[XB_TMO])) break; if (_sp > XB_SPIN_CAP) { atomicAdd(&(bar)[XB_TMO], 1u); break; } } } } while (0)
; __device__ __forceinline__ void xcd_barrier(const XcdBarrier& b, bool leader) {
;     ...
;         const unsigned old = xb_add(&bar[XB_XSUB(b.x)], 1u);
;         const unsigned gen = old / nloc;
;         if (old + 1u == (gen + 1u) * nloc) {
;             __builtin_amdgcn_fence(__ATOMIC_RELEASE, "agent");
;             asm volatile("s_waitcnt vmcnt(0)" ::: "memory");
;             const unsigned og = xb_add(&bar[XB_TOP], 1u);
;             const unsigned tg = og / nx;
;             if (og + 1u == (tg + 1u) * nx) xb_add(&bar[XB_TOPGEN], 1u);
;             else XB_SPIN(xb_ld(&bar[XB_TOPGEN]) == tg, bar);
;             __builtin_amdgcn_fence(__ATOMIC_ACQUIRE, "agent");
;             xb_add(&bar[XB_XGEN(b.x)], 1u);
;             asm volatile("s_waitcnt vmcnt(0)" ::: "memory");
;         } else {
;             XB_SPIN(xb_ld(&bar[XB_XGEN(b.x)]) == gen, bar);
;             __builtin_amdgcn_fence(__ATOMIC_ACQUIRE, "agent");
;             asm volatile("s_waitcnt vmcnt(0)" ::: "memory");
;         }
.LBB0_157:
	s_or_b64 exec, exec, s[10:11]
.LBB0_158:
	s_andn2_saveexec_b64 s[8:9], s[8:9]
	s_cbranch_execz .LBB0_178
	s_mov_b64 s[8:9], exec
	buffer_wbl2 sc1
	s_waitcnt lgkmcnt(0)
	s_waitcnt vmcnt(0)
	v_mbcnt_lo_u32_b32 v1, s8, 0
	v_mbcnt_hi_u32_b32 v1, s9, v1
	v_cmp_eq_u32_e32 vcc, 0, v1
	s_and_saveexec_b64 s[10:11], vcc
	s_cbranch_execz .LBB0_161
	s_bcnt1_i32_b64 s8, s[8:9]
	v_mov_b32_e32 v2, 0x3000
	v_mov_b32_e32 v3, s8
	global_atomic_add v2, v2, v3, s[76:77] offset:1024 sc0
.LBB0_161:
	s_or_b64 exec, exec, s[10:11]
	buffer_inv sc1
	v_cvt_f32_u32_e32 v3, v0
	s_waitcnt vmcnt(0)
	v_readfirstlane_b32 s8, v2
	s_add_u32 s10, s76, 0x3500
	s_addc_u32 s11, s77, 0
	v_rcp_iflag_f32_e32 v3, v3
	v_add_u32_e32 v1, s8, v1
	v_add_u32_e32 v4, 1, v1
	s_mov_b64 s[14:15], -1
	v_mul_f32_e32 v2, 0x4f7ffffe, v3
	v_cvt_u32_f32_e32 v2, v2
	v_sub_u32_e32 v3, 0, v0
	v_mul_lo_u32 v3, v3, v2
	v_mul_hi_u32 v3, v2, v3
	v_add_u32_e32 v2, v2, v3
	v_mul_hi_u32 v2, v1, v2
	v_mul_lo_u32 v3, v2, v0
	v_sub_u32_e32 v1, v1, v3
	v_add_u32_e32 v5, 1, v2
	v_cmp_ge_u32_e32 vcc, v1, v0
	v_sub_u32_e32 v3, v1, v0
	s_nop 0
	v_cndmask_b32_e32 v2, v2, v5, vcc
	v_cndmask_b32_e32 v1, v1, v3, vcc
	v_add_u32_e32 v3, 1, v2
	v_cmp_ge_u32_e32 vcc, v1, v0
	s_nop 1
	v_cndmask_b32_e32 v2, v2, v3, vcc
	v_mul_lo_u32 v1, v0, v2
	v_add_u32_e32 v0, v1, v0
	v_mov_b32_e32 v2, v0
	v_cmp_ne_u32_e32 vcc, v4, v0
	v_mov_b64_e32 v[0:1], s[10:11]
	s_and_saveexec_b64 s[8:9], vcc
	s_cbranch_execz .LBB0_173
	v_mov_b32_e32 v0, 0
	global_load_dword v1, v0, s[10:11] offset:-256 sc1
	s_mov_b64 s[18:19], 0
	s_waitcnt vmcnt(0)
	v_cmp_lt_u32_e32 vcc, v1, v2
	s_and_saveexec_b64 s[16:17], vcc
	s_cbranch_execz .LBB0_172
	v_mov_b32_e32 v239, v1
	s_add_u32 s14, s76, 0x200
	s_addc_u32 s15, s77, 0
	s_mov_b32 s13, 1
	s_branch .LBB0_165

; __device__ __forceinline__ unsigned xb_ld(unsigned* p)              { return __hip_atomic_load(p, __ATOMIC_RELAXED, __HIP_MEMORY_SCOPE_AGENT); }
; __device__ __forceinline__ unsigned xb_add(unsigned* p, unsigned v) { return __hip_atomic_fetch_add(p, v, __ATOMIC_RELAXED, __HIP_MEMORY_SCOPE_AGENT); }
; #define XB_SPIN(cond, bar) do { unsigned _sp = 0; while (cond) { __builtin_amdgcn_s_sleep(1); \
;     if ((++_sp & 255u) == 0u) { if (xb_ld(&(bar)[XB_TMO])) break; if (_sp > XB_SPIN_CAP) { atomicAdd(&(bar)[XB_TMO], 1u); break; } } } } while (0)
; __device__ __forceinline__ void xcd_barrier(const XcdBarrier& b, bool leader) {
;     ...
;             const unsigned og = xb_add(&bar[XB_TOP], 1u);
;             const unsigned tg = og / nx;
;             if (og + 1u == (tg + 1u) * nx) xb_add(&bar[XB_TOPGEN], 1u);
;             else XB_SPIN(xb_ld(&bar[XB_TOPGEN]) == tg, bar);
.LBB0_169:
	global_load_dword v239, v0, s[10:11] offset:-256 sc1
	s_add_i32 s13, s13, 1
	s_mov_b64 s[22:23], -1
	s_waitcnt vmcnt(1)
	v_cmp_ge_u32_e32 vcc, v239, v2
	s_orn2_b64 s[26:27], vcc, exec
	s_branch .LBB0_164

; __device__ __forceinline__ unsigned xb_ld(unsigned* p)              { return __hip_atomic_load(p, __ATOMIC_RELAXED, __HIP_MEMORY_SCOPE_AGENT); }
; __device__ __forceinline__ unsigned xb_add(unsigned* p, unsigned v) { return __hip_atomic_fetch_add(p, v, __ATOMIC_RELAXED, __HIP_MEMORY_SCOPE_AGENT); }
; #define XB_SPIN(cond, bar) do { unsigned _sp = 0; while (cond) { __builtin_amdgcn_s_sleep(1); \
;     if ((++_sp & 255u) == 0u) { if (xb_ld(&(bar)[XB_TMO])) break; if (_sp > XB_SPIN_CAP) { atomicAdd(&(bar)[XB_TMO], 1u); break; } } } } while (0)
;     __device__ bool next(int i, Unit& u) const {
;         const long L = (long)i * G + c; if (L >= nwg) return false;
;         int wgid = (int)L; { const int q = nwg / NXCD, r = nwg % NXCD, xcd = wgid % NXCD, off = wgid / NXCD; wgid = (xcd < r ? xcd * (q + 1) : r * (q + 1) + (xcd - r) * q) + off; }
;         const int nig = WGM * nN, gid = wgid / nig, fm = gid * WGM, gsz = (nM - fm) < WGM ? (nM - fm) : WGM;
;         u.pm = fm + ((wgid % nig) % gsz); u.pn = (wgid % nig) / gsz; u.sub = 0; return true;
; __device__ __forceinline__ void xcd_barrier(const XcdBarrier& b, bool leader) {
;     ...
;             xb_add(&bar[XB_XGEN(b.x)], 1u);
;             asm volatile("s_waitcnt vmcnt(0)" ::: "memory");
;         } else {
;             XB_SPIN(xb_ld(&bar[XB_XGEN(b.x)]) == gen, bar);
;             __builtin_amdgcn_fence(__ATOMIC_ACQUIRE, "agent");
;             asm volatile("s_waitcnt vmcnt(0)" ::: "memory");
;         }
;     }
;     __syncthreads();
.LBB0_175:
	s_or_b64 exec, exec, s[8:9]
	s_mov_b64 s[8:9], exec
	v_mbcnt_lo_u32_b32 v0, s8, 0
	v_mbcnt_hi_u32_b32 v0, s9, v0
	v_cmp_eq_u32_e32 vcc, 0, v0
	s_and_saveexec_b64 s[10:11], vcc
	s_cbranch_execz .LBB0_177
	s_bcnt1_i32_b64 s8, s[8:9]
	v_mov_b32_e32 v0, 0x2000
	v_mov_b32_e32 v1, s8
.LBB0_177:
	s_or_b64 exec, exec, s[10:11]
.LBB0_178:
	s_or_b64 exec, exec, s[4:5]
	s_waitcnt lgkmcnt(0)
	s_barrier
	s_load_dwordx2 s[4:5], s[0:1], 0x48
	s_cmp_lt_i32 s2, 36
	v_mov_b32_e32 v8, v166
	s_cselect_b64 s[6:7], -1, 0
	s_cmp_gt_i32 s2, 35
	s_cbranch_scc1 .LBB0_184
	s_ashr_i32 s8, s2, 31
	s_lshr_b32 s8, s8, 29
	s_add_i32 s10, s2, s8
	s_and_b32 s8, s10, -8
	s_sub_i32 s11, s2, s8
	s_cmp_gt_i32 s11, 3
	s_cbranch_scc0 .LBB0_181
	s_lshl_b32 s8, s11, 2
	s_add_i32 s13, s8, 4
	s_cbranch_execz .LBB0_182
	s_branch .LBB0_183

; __device__ __forceinline__ unsigned xb_ld(unsigned* p)              { return __hip_atomic_load(p, __ATOMIC_RELAXED, __HIP_MEMORY_SCOPE_AGENT); }
; __device__ __forceinline__ unsigned xb_add(unsigned* p, unsigned v) { return __hip_atomic_fetch_add(p, v, __ATOMIC_RELAXED, __HIP_MEMORY_SCOPE_AGENT); }
; #define XB_SPIN(cond, bar) do { unsigned _sp = 0; while (cond) { __builtin_amdgcn_s_sleep(1); \
;     if ((++_sp & 255u) == 0u) { if (xb_ld(&(bar)[XB_TMO])) break; if (_sp > XB_SPIN_CAP) { atomicAdd(&(bar)[XB_TMO], 1u); break; } } } } while (0)
; __device__ __forceinline__ void xcd_barrier(const XcdBarrier& b, bool leader) {
;     ...
;         const unsigned old = xb_add(&bar[XB_XSUB(b.x)], 1u);
;         const unsigned gen = old / nloc;
;         if (old + 1u == (gen + 1u) * nloc) {
;             __builtin_amdgcn_fence(__ATOMIC_RELEASE, "agent");
;             asm volatile("s_waitcnt vmcnt(0)" ::: "memory");
;             const unsigned og = xb_add(&bar[XB_TOP], 1u);
;             const unsigned tg = og / nx;
;             if (og + 1u == (tg + 1u) * nx) xb_add(&bar[XB_TOPGEN], 1u);
;             else XB_SPIN(xb_ld(&bar[XB_TOPGEN]) == tg, bar);
;             __builtin_amdgcn_fence(__ATOMIC_ACQUIRE, "agent");
;             xb_add(&bar[XB_XGEN(b.x)], 1u);
;             asm volatile("s_waitcnt vmcnt(0)" ::: "memory");
;         } else {
;             XB_SPIN(xb_ld(&bar[XB_XGEN(b.x)]) == gen, bar);
.LBB0_363:
	s_or_b64 exec, exec, s[10:11]
	v_cvt_f32_u32_e32 v4, v2
	s_waitcnt vmcnt(0)
	v_readfirstlane_b32 s8, v3
	v_sub_u32_e32 v3, 0, v2
	v_rcp_iflag_f32_e32 v4, v4
	v_add_u32_e32 v5, s8, v1
	v_mul_f32_e32 v4, 0x4f7ffffe, v4
	v_cvt_u32_f32_e32 v4, v4
	v_mul_lo_u32 v1, v3, v4
	v_mul_hi_u32 v1, v4, v1
	v_add_u32_e32 v1, v4, v1
	v_mul_hi_u32 v1, v5, v1
	v_mul_lo_u32 v3, v1, v2
	v_sub_u32_e32 v3, v5, v3
	v_add_u32_e32 v4, 1, v1
	v_cmp_ge_u32_e32 vcc, v3, v2
	s_nop 1
	v_cndmask_b32_e32 v1, v1, v4, vcc
	v_sub_u32_e32 v4, v3, v2
	v_cndmask_b32_e32 v3, v3, v4, vcc
	v_add_u32_e32 v4, 1, v1
	v_cmp_ge_u32_e32 vcc, v3, v2
	v_add_u32_e32 v3, 1, v5
	s_nop 0
	v_cndmask_b32_e32 v1, v1, v4, vcc
	v_mul_lo_u32 v4, v2, v1
	v_add_u32_e32 v2, v4, v2
	v_cmp_ne_u32_e32 vcc, v3, v2
	s_and_saveexec_b64 s[8:9], vcc
	s_xor_b64 s[8:9], exec, s[8:9]
	s_cbranch_execz .LBB0_377
	buffer_inv sc1
	s_waitcnt lgkmcnt(0)
	v_add_u32_e32 v1, 1, v1
	v_mul_lo_u32 v1, v1, v0
	v_mov_b32_e32 v0, 0x3000
	global_load_dword v0, v0, s[76:77] offset:1024 sc1
	s_add_u32 s12, s76, 0x3400
	s_addc_u32 s13, s77, 0
	s_waitcnt vmcnt(0)
	v_cmp_lt_u32_e32 vcc, v0, v1
	s_and_saveexec_b64 s[10:11], vcc
	s_cbranch_execz .LBB0_376
	s_mov_b32 s24, 1
	s_mov_b64 s[14:15], 0
	v_mov_b32_e32 v239, v0
	v_mov_b32_e32 v0, 0
	s_branch .LBB0_367

; __device__ __forceinline__ unsigned xb_ld(unsigned* p)              { return __hip_atomic_load(p, __ATOMIC_RELAXED, __HIP_MEMORY_SCOPE_AGENT); }
; #define XB_SPIN(cond, bar) do { unsigned _sp = 0; while (cond) { __builtin_amdgcn_s_sleep(1); \
;     if ((++_sp & 255u) == 0u) { if (xb_ld(&(bar)[XB_TMO])) break; if (_sp > XB_SPIN_CAP) { atomicAdd(&(bar)[XB_TMO], 1u); break; } } } } while (0)
; __device__ __forceinline__ void xcd_barrier(const XcdBarrier& b, bool leader) {
;     ...
;         } else {
;             XB_SPIN(xb_ld(&bar[XB_XGEN(b.x)]) == gen, bar);
.LBB0_371:
	global_load_dword v239, v0, s[12:13] sc1
	s_add_i32 s24, s24, 1
	s_mov_b64 s[20:21], -1
	s_waitcnt vmcnt(1)
	v_cmp_ge_u32_e32 vcc, v239, v1
	s_orn2_b64 s[18:19], vcc, exec
	s_branch .LBB0_366

; __device__ __forceinline__ unsigned xb_ld(unsigned* p)              { return __hip_atomic_load(p, __ATOMIC_RELAXED, __HIP_MEMORY_SCOPE_AGENT); }
; __device__ __forceinline__ unsigned xb_add(unsigned* p, unsigned v) { return __hip_atomic_fetch_add(p, v, __ATOMIC_RELAXED, __HIP_MEMORY_SCOPE_AGENT); }
; #define XB_SPIN(cond, bar) do { unsigned _sp = 0; while (cond) { __builtin_amdgcn_s_sleep(1); \
;     if ((++_sp & 255u) == 0u) { if (xb_ld(&(bar)[XB_TMO])) break; if (_sp > XB_SPIN_CAP) { atomicAdd(&(bar)[XB_TMO], 1u); break; } } } } while (0)
; __device__ __forceinline__ void xcd_barrier(const XcdBarrier& b, bool leader) {
;     ...
;         const unsigned old = xb_add(&bar[XB_XSUB(b.x)], 1u);
;         const unsigned gen = old / nloc;
;         if (old + 1u == (gen + 1u) * nloc) {
;             __builtin_amdgcn_fence(__ATOMIC_RELEASE, "agent");
;             asm volatile("s_waitcnt vmcnt(0)" ::: "memory");
;             const unsigned og = xb_add(&bar[XB_TOP], 1u);
;             const unsigned tg = og / nx;
;             if (og + 1u == (tg + 1u) * nx) xb_add(&bar[XB_TOPGEN], 1u);
;             else XB_SPIN(xb_ld(&bar[XB_TOPGEN]) == tg, bar);
;             __builtin_amdgcn_fence(__ATOMIC_ACQUIRE, "agent");
;             xb_add(&bar[XB_XGEN(b.x)], 1u);
;             asm volatile("s_waitcnt vmcnt(0)" ::: "memory");
;         } else {
;             XB_SPIN(xb_ld(&bar[XB_XGEN(b.x)]) == gen, bar);
;             __builtin_amdgcn_fence(__ATOMIC_ACQUIRE, "agent");
;             asm volatile("s_waitcnt vmcnt(0)" ::: "memory");
;         }
.LBB0_376:
	s_or_b64 exec, exec, s[10:11]
.LBB0_377:
	s_andn2_saveexec_b64 s[8:9], s[8:9]
	s_cbranch_execz .LBB0_397
	s_mov_b64 s[8:9], exec
	buffer_wbl2 sc1
	s_waitcnt lgkmcnt(0)
	s_waitcnt vmcnt(0)
	v_mbcnt_lo_u32_b32 v1, s8, 0
	v_mbcnt_hi_u32_b32 v1, s9, v1
	v_cmp_eq_u32_e32 vcc, 0, v1
	s_and_saveexec_b64 s[10:11], vcc
	s_cbranch_execz .LBB0_380
	s_bcnt1_i32_b64 s8, s[8:9]
	v_mov_b32_e32 v2, 0x3000
	v_mov_b32_e32 v3, s8
	global_atomic_add v2, v2, v3, s[76:77] offset:1024 sc0
.LBB0_380:
	s_or_b64 exec, exec, s[10:11]
	buffer_inv sc1
	v_cvt_f32_u32_e32 v3, v0
	s_waitcnt vmcnt(0)
	v_readfirstlane_b32 s8, v2
	s_add_u32 s10, s76, 0x3500
	s_addc_u32 s11, s77, 0
	v_rcp_iflag_f32_e32 v3, v3
	v_add_u32_e32 v1, s8, v1
	v_add_u32_e32 v4, 1, v1
	s_mov_b64 s[12:13], -1
	v_mul_f32_e32 v2, 0x4f7ffffe, v3
	v_cvt_u32_f32_e32 v2, v2
	v_sub_u32_e32 v3, 0, v0
	v_mul_lo_u32 v3, v3, v2
	v_mul_hi_u32 v3, v2, v3
	v_add_u32_e32 v2, v2, v3
	v_mul_hi_u32 v2, v1, v2
	v_mul_lo_u32 v3, v2, v0
	v_sub_u32_e32 v1, v1, v3
	v_add_u32_e32 v5, 1, v2
	v_cmp_ge_u32_e32 vcc, v1, v0
	v_sub_u32_e32 v3, v1, v0
	s_nop 0
	v_cndmask_b32_e32 v2, v2, v5, vcc
	v_cndmask_b32_e32 v1, v1, v3, vcc
	v_add_u32_e32 v3, 1, v2
	v_cmp_ge_u32_e32 vcc, v1, v0
	s_nop 1
	v_cndmask_b32_e32 v2, v2, v3, vcc
	v_mul_lo_u32 v1, v0, v2
	v_add_u32_e32 v0, v1, v0
	v_mov_b32_e32 v2, v0
	v_cmp_ne_u32_e32 vcc, v4, v0
	v_mov_b64_e32 v[0:1], s[10:11]
	s_and_saveexec_b64 s[8:9], vcc
	s_cbranch_execz .LBB0_392
	v_mov_b32_e32 v0, 0
	global_load_dword v1, v0, s[10:11] offset:-256 sc1
	s_mov_b64 s[16:17], 0
	s_waitcnt vmcnt(0)
	v_cmp_lt_u32_e32 vcc, v1, v2
	s_and_saveexec_b64 s[14:15], vcc
	s_cbranch_execz .LBB0_391
	v_mov_b32_e32 v239, v1
	s_add_u32 s12, s76, 0x200
	s_addc_u32 s13, s77, 0
	s_mov_b32 s26, 1
	s_branch .LBB0_384

; __device__ __forceinline__ unsigned xb_ld(unsigned* p)              { return __hip_atomic_load(p, __ATOMIC_RELAXED, __HIP_MEMORY_SCOPE_AGENT); }
; __device__ __forceinline__ unsigned xb_add(unsigned* p, unsigned v) { return __hip_atomic_fetch_add(p, v, __ATOMIC_RELAXED, __HIP_MEMORY_SCOPE_AGENT); }
; #define XB_SPIN(cond, bar) do { unsigned _sp = 0; while (cond) { __builtin_amdgcn_s_sleep(1); \
;     if ((++_sp & 255u) == 0u) { if (xb_ld(&(bar)[XB_TMO])) break; if (_sp > XB_SPIN_CAP) { atomicAdd(&(bar)[XB_TMO], 1u); break; } } } } while (0)
; __device__ __forceinline__ void xcd_barrier(const XcdBarrier& b, bool leader) {
;     ...
;             const unsigned og = xb_add(&bar[XB_TOP], 1u);
;             const unsigned tg = og / nx;
;             if (og + 1u == (tg + 1u) * nx) xb_add(&bar[XB_TOPGEN], 1u);
;             else XB_SPIN(xb_ld(&bar[XB_TOPGEN]) == tg, bar);
.LBB0_388:
	global_load_dword v239, v0, s[10:11] offset:-256 sc1
	s_add_i32 s26, s26, 1
	s_mov_b64 s[20:21], -1
	s_waitcnt vmcnt(1)
	v_cmp_ge_u32_e32 vcc, v239, v2
	s_orn2_b64 s[24:25], vcc, exec
	s_branch .LBB0_383

; __device__ __forceinline__ unsigned pk2(float lo, float hi) { f32x2_t v = {lo, hi}; bf16x2_t b = __builtin_convertvector(v, bf16x2_t); return __builtin_bit_cast(unsigned, b); }
; __device__ __forceinline__ float rsq_f(float x) { return __builtin_amdgcn_rsqf(x); }
; __device__ __forceinline__ float* karg_out() { return *(volatile KAS fptr_t*)((const KAS char*)__builtin_amdgcn_kernarg_segment_ptr() + 256); }
; __device__ __forceinline__ unsigned char* karg_ws() { return *(volatile KAS ucptr_t*)((const KAS char*)__builtin_amdgcn_kernarg_segment_ptr() + 264); }
; #define INP(k) karg_in(k)
; #define lane opq(lane_now())
; template <int MODE>
; __device__ __forceinline__ void norm_mod_pass(const Params& P, const float* gvec, int ish, int gw, int NGW, int lane) {
;     const float* ada = (const float*)(karg_ws() + WS_ADA); bf16* H = (bf16*)(karg_ws() + WS_H);
;     const float* xp = INP(0); const float* xs = INP(1); const float* X = karg_out();
;     for (int row0 = 2 * gw; row0 < M; row0 += 2 * NGW) {
;         f32x4 v[2][4]; float s[2] = {0.f, 0.f};
; #pragma unroll
;         for (int u = 0; u < 2; ++u) { const int row = row0 + u;
;             const float* xr = MODE == 0 ? (row < MPR ? xp + (size_t)row * D : xs + (size_t)(row - MPR) * D) : X + (size_t)row * D;
; #pragma unroll
;             for (int j = 0; j < 4; ++j) v[u][j] = *(const f32x4*)(xr + 4 * (lane + 64 * j)); }
; #pragma unroll
;         for (int u = 0; u < 2; ++u)
; #pragma unroll
;             for (int j = 0; j < 4; ++j) s[u] += (v[u][j][0] * v[u][j][0] + v[u][j][1] * v[u][j][1]) + (v[u][j][2] * v[u][j][2] + v[u][j][3] * v[u][j][3]);
;         s[0] = wave_sum(s[0]); s[1] = wave_sum(s[1]);
; #pragma unroll
;         for (int u = 0; u < 2; ++u) { const int row = row0 + u; const float rstd = rsq_f(s[u] * (1.f / D) + EPS);
;             const float* sh = ada + (size_t)cond_of_row(row) * NADA + ish * D; const float* sc = sh + D;
; #pragma unroll
;             for (int j = 0; j < 4; ++j) { const int col = 4 * (lane + 64 * j); const f32x4 g = *(const f32x4*)(gvec + col), a = *(const f32x4*)(sc + col), bb = *(const f32x4*)(sh + col);
;                 const f32x4 y = (v[u][j] * rstd * g) * (a + 1.f) + bb; u32x2 o; o.x = pk2(y[0], y[1]); o.y = pk2(y[2], y[3]); *(u32x2*)(H + (size_t)row * D + col) = o; } }
.LBB0_396:
	s_or_b64 exec, exec, s[10:11]
.LBB0_397:
	s_or_b64 exec, exec, s[4:5]
	s_waitcnt lgkmcnt(0)
	v_mov_b32_e32 v0, v166
	s_barrier
	s_load_dwordx2 s[12:13], s[0:1], 0x50
	s_load_dwordx2 s[8:9], s[0:1], 0x108
	s_load_dwordx2 s[16:17], s[0:1], 0x108
	s_load_dwordx2 s[4:5], s[0:1], 0x0
	s_load_dwordx2 s[6:7], s[0:1], 0x8
	s_load_dwordx2 s[10:11], s[0:1], 0x100
	s_cmpk_gt_i32 s72, 0x203f
	s_cbranch_scc1 .LBB0_402
	s_waitcnt lgkmcnt(0)
	s_add_u32 s28, s8, 0x2900000
	s_addc_u32 s29, s9, 0
	s_lshl_b32 s8, s72, 1
	v_lshlrev_b32_e32 v20, 2, v0
	s_lshl_b32 s10, s78, 4
	v_ashrrev_i32_e32 v21, 31, v20
	s_ashr_i32 s9, s8, 31
	v_lshl_add_u64 v[22:23], v[20:21], 2, s[12:13]
	s_ashr_i32 s11, s10, 31
	s_lshl_b64 s[12:13], s[8:9], 12
	s_add_u32 s12, s4, s12
	s_addc_u32 s13, s5, s13
	s_add_u32 s12, s12, 0x1000
	v_lshlrev_b64 v[6:7], 1, v[20:21]
	s_addc_u32 s13, s13, 0
	s_lshl_b64 s[14:15], s[10:11], 12
	s_lshl_b64 s[20:21], s[8:9], 11
	v_lshl_add_u64 v[8:9], s[16:17], 0, v[6:7]
	s_add_u32 s16, s16, s20
	v_add_u32_e32 v0, 0x100, v20
	v_add_u32_e32 v2, 0x200, v20
	v_add_u32_e32 v4, 0x300, v20
	s_addc_u32 s17, s17, s21
	v_ashrrev_i32_e32 v1, 31, v0
	v_ashrrev_i32_e32 v3, 31, v2
	v_ashrrev_i32_e32 v5, 31, v4
	s_mov_b64 s[18:19], 0x3000000
	v_lshl_add_u64 v[6:7], s[16:17], 0, v[6:7]
	v_lshl_add_u64 v[24:25], v[8:9], 0, s[18:19]
	v_lshl_add_u64 v[26:27], v[6:7], 0, s[18:19]
	s_lshl_b64 s[16:17], s[10:11], 11
	s_mov_b32 s19, 0
	v_lshlrev_b64 v[28:29], 2, v[20:21]
	v_mov_b32_e32 v36, 0x358637bd
	v_lshlrev_b64 v[30:31], 2, v[0:1]
	v_lshlrev_b64 v[32:33], 2, v[2:3]
	v_lshlrev_b64 v[34:35], 2, v[4:5]
	s_branch .LBB0_400

; __device__ __forceinline__ unsigned xb_ld(unsigned* p)              { return __hip_atomic_load(p, __ATOMIC_RELAXED, __HIP_MEMORY_SCOPE_AGENT); }
; __device__ __forceinline__ unsigned xb_add(unsigned* p, unsigned v) { return __hip_atomic_fetch_add(p, v, __ATOMIC_RELAXED, __HIP_MEMORY_SCOPE_AGENT); }
; #define XB_SPIN(cond, bar) do { unsigned _sp = 0; while (cond) { __builtin_amdgcn_s_sleep(1); \
;     if ((++_sp & 255u) == 0u) { if (xb_ld(&(bar)[XB_TMO])) break; if (_sp > XB_SPIN_CAP) { atomicAdd(&(bar)[XB_TMO], 1u); break; } } } } while (0)
; __device__ __forceinline__ void xcd_barrier(const XcdBarrier& b, bool leader) {
;     ...
;         const unsigned old = xb_add(&bar[XB_XSUB(b.x)], 1u);
;         const unsigned gen = old / nloc;
;         if (old + 1u == (gen + 1u) * nloc) {
;             __builtin_amdgcn_fence(__ATOMIC_RELEASE, "agent");
;             asm volatile("s_waitcnt vmcnt(0)" ::: "memory");
;             const unsigned og = xb_add(&bar[XB_TOP], 1u);
;             const unsigned tg = og / nx;
;             if (og + 1u == (tg + 1u) * nx) xb_add(&bar[XB_TOPGEN], 1u);
;             else XB_SPIN(xb_ld(&bar[XB_TOPGEN]) == tg, bar);
;             __builtin_amdgcn_fence(__ATOMIC_ACQUIRE, "agent");
;             xb_add(&bar[XB_XGEN(b.x)], 1u);
;             asm volatile("s_waitcnt vmcnt(0)" ::: "memory");
;         } else {
;             XB_SPIN(xb_ld(&bar[XB_XGEN(b.x)]) == gen, bar);
;             __builtin_amdgcn_fence(__ATOMIC_ACQUIRE, "agent");
;             asm volatile("s_waitcnt vmcnt(0)" ::: "memory");
;         }
.LBB0_435:
	s_or_b64 exec, exec, s[10:11]
.LBB0_436:
	s_andn2_saveexec_b64 s[8:9], s[8:9]
	s_cbranch_execz .LBB0_456
	s_mov_b64 s[8:9], exec
	buffer_wbl2 sc1
	s_waitcnt lgkmcnt(0)
	s_waitcnt vmcnt(0)
	v_mbcnt_lo_u32_b32 v1, s8, 0
	v_mbcnt_hi_u32_b32 v1, s9, v1
	v_cmp_eq_u32_e32 vcc, 0, v1
	s_and_saveexec_b64 s[10:11], vcc
	s_cbranch_execz .LBB0_439
	s_bcnt1_i32_b64 s8, s[8:9]
	v_mov_b32_e32 v2, 0x3000
	v_mov_b32_e32 v3, s8
	global_atomic_add v2, v2, v3, s[76:77] offset:1024 sc0

;     __device__ bool next(int i, Unit& u) const { const bool ok = base.next(i >> 1, u); u.sub = i & 1; return ok; }
;     __device__ bool next(int i, Unit& u) const {
;         const long L = (long)i * G + c; if (L >= nwg) return false;
;         int wgid = (int)L; { const int q = nwg / NXCD, r = nwg % NXCD, xcd = wgid % NXCD, off = wgid / NXCD; wgid = (xcd < r ? xcd * (q + 1) : r * (q + 1) + (xcd - r) * q) + off; }
;         const int nig = WGM * nN, gid = wgid / nig, fm = gid * WGM, gsz = (nM - fm) < WGM ? (nM - fm) : WGM;
;         u.pm = fm + ((wgid % nig) % gsz); u.pn = (wgid % nig) / gsz; u.sub = 0; return true;
; __global__ void __launch_bounds__(NTHR, 2) fwd_megakernel(Params P) {
;     ...
;     { pg8::Gemm g{H, (const bf16*)(ws + WS_WUP1), nullptr, nullptr, D}; pg8::StaticOrder S; S.init(MPAD, 2 * FF, G, wg);
;       EpiSwiglu E{ACT}; pg8::gemm_phase(lds, g, S, E, wave); }
.LBB0_455:
	s_or_b64 exec, exec, s[10:11]
.LBB0_456:
	s_or_b64 exec, exec, s[4:5]
	s_cmpk_lt_i32 s2, 0x596
	v_mov_b32_e32 v8, v166
	s_cselect_b64 s[4:5], -1, 0
	s_cmpk_gt_i32 s2, 0x595
	s_waitcnt lgkmcnt(0)
	s_barrier
	s_cbranch_scc1 .LBB0_462
	s_ashr_i32 s6, s2, 31
	s_lshr_b32 s6, s6, 29
	s_add_i32 s8, s2, s6
	s_and_b32 s6, s8, -8
	s_sub_i32 s9, s2, s6
	s_cmp_gt_i32 s9, 5
	s_cbranch_scc0 .LBB0_459
	s_mul_i32 s6, s9, 0xb2
	s_add_i32 s10, s6, 6
	s_cbranch_execz .LBB0_460
	s_branch .LBB0_461

; __device__ __forceinline__ unsigned xb_ld(unsigned* p)              { return __hip_atomic_load(p, __ATOMIC_RELAXED, __HIP_MEMORY_SCOPE_AGENT); }
; __device__ __forceinline__ unsigned xb_add(unsigned* p, unsigned v) { return __hip_atomic_fetch_add(p, v, __ATOMIC_RELAXED, __HIP_MEMORY_SCOPE_AGENT); }
; #define XB_SPIN(cond, bar) do { unsigned _sp = 0; while (cond) { __builtin_amdgcn_s_sleep(1); \
;     if ((++_sp & 255u) == 0u) { if (xb_ld(&(bar)[XB_TMO])) break; if (_sp > XB_SPIN_CAP) { atomicAdd(&(bar)[XB_TMO], 1u); break; } } } } while (0)
; __device__ __forceinline__ void xcd_barrier(const XcdBarrier& b, bool leader) {
;     ...
;         const unsigned old = xb_add(&bar[XB_XSUB(b.x)], 1u);
;         const unsigned gen = old / nloc;
;         if (old + 1u == (gen + 1u) * nloc) {
;             __builtin_amdgcn_fence(__ATOMIC_RELEASE, "agent");
;             asm volatile("s_waitcnt vmcnt(0)" ::: "memory");
;             const unsigned og = xb_add(&bar[XB_TOP], 1u);
;             const unsigned tg = og / nx;
;             if (og + 1u == (tg + 1u) * nx) xb_add(&bar[XB_TOPGEN], 1u);
;             else XB_SPIN(xb_ld(&bar[XB_TOPGEN]) == tg, bar);
;             __builtin_amdgcn_fence(__ATOMIC_ACQUIRE, "agent");
;             xb_add(&bar[XB_XGEN(b.x)], 1u);
;             asm volatile("s_waitcnt vmcnt(0)" ::: "memory");
;         } else {
;             XB_SPIN(xb_ld(&bar[XB_XGEN(b.x)]) == gen, bar);
;             __builtin_amdgcn_fence(__ATOMIC_ACQUIRE, "agent");
;             asm volatile("s_waitcnt vmcnt(0)" ::: "memory");
;         }
.LBB0_529:
	s_or_b64 exec, exec, s[10:11]
.LBB0_530:
	s_andn2_saveexec_b64 s[8:9], s[8:9]
	s_cbranch_execz .LBB0_550
	s_mov_b64 s[8:9], exec
	buffer_wbl2 sc1
	s_waitcnt lgkmcnt(0)
	s_waitcnt vmcnt(0)
	v_mbcnt_lo_u32_b32 v1, s8, 0
	v_mbcnt_hi_u32_b32 v1, s9, v1
	v_cmp_eq_u32_e32 vcc, 0, v1
	s_and_saveexec_b64 s[10:11], vcc
	s_cbranch_execz .LBB0_533
	s_bcnt1_i32_b64 s8, s[8:9]
	v_mov_b32_e32 v2, 0x3000
	v_mov_b32_e32 v3, s8
	global_atomic_add v2, v2, v3, s[76:77] offset:1024 sc0

; #define LAS __attribute__((address_space(3)))
;     __device__ bool next(int i, Unit& u) const { const bool ok = base.next(i >> 1, u); u.sub = i & 1; return ok; }
; __device__ __forceinline__ float* karg_out() { return *(volatile KAS fptr_t*)((const KAS char*)__builtin_amdgcn_kernarg_segment_ptr() + 256); }
; #define INP(k) karg_in(k)
;     __device__ bool next(int i, Unit& u) const {
;         const long L = (long)i * G + c; if (L >= nwg) return false;
;         int wgid = (int)L; { const int q = nwg / NXCD, r = nwg % NXCD, xcd = wgid % NXCD, off = wgid / NXCD; wgid = (xcd < r ? xcd * (q + 1) : r * (q + 1) + (xcd - r) * q) + off; }
;         const int nig = WGM * nN, gid = wgid / nig, fm = gid * WGM, gsz = (nM - fm) < WGM ? (nM - fm) : WGM;
;         u.pm = fm + ((wgid % nig) % gsz); u.pn = (wgid % nig) / gsz; u.sub = 0; return true;
; __global__ void __launch_bounds__(NTHR, 2) fwd_megakernel(Params P) {
;     ...
;     { pg8::Gemm g{ACT, (const bf16*)(ws + WS_WDN1), nullptr, nullptr, FF}; pg8::StaticOrder S; S.init(MPR, D, G, wg);
;       EpiResidNorm<0> E{karg_out(), INP(0), ADA + 2 * D, 0.5f, INP(13), ADA + 3 * D, H, (float*)(ws + WS_PART), (unsigned*)(ws + WS_CNT), (LAS float*)(lds + 131072)}; pg8::gemm_phase(lds, g, S, E, wave);
.LBB0_549:
	s_or_b64 exec, exec, s[10:11]
.LBB0_550:
	s_or_b64 exec, exec, s[4:5]
	s_waitcnt lgkmcnt(0)
	s_barrier
	s_load_dwordx2 s[14:15], s[0:1], 0x100
	s_load_dwordx2 s[8:9], s[0:1], 0x0
	s_load_dwordx2 s[16:17], s[0:1], 0x68
	s_cmpk_lt_i32 s2, 0x100
	v_mov_b32_e32 v8, v166
	s_cselect_b64 s[4:5], -1, 0
	s_cmpk_gt_i32 s2, 0xff
	s_cbranch_scc1 .LBB0_556
	s_ashr_i32 s6, s2, 31
	s_lshr_b32 s6, s6, 29
	s_add_i32 s10, s2, s6
	s_and_b32 s6, s10, -8
	s_sub_i32 s11, s2, s6
	s_cmp_gt_i32 s11, -1
	s_cbranch_scc0 .LBB0_553
	s_lshl_b32 s12, s11, 5
	s_cbranch_execz .LBB0_554
	s_branch .LBB0_555

; __device__ __forceinline__ unsigned xb_ld(unsigned* p)              { return __hip_atomic_load(p, __ATOMIC_RELAXED, __HIP_MEMORY_SCOPE_AGENT); }
; __device__ __forceinline__ unsigned xb_add(unsigned* p, unsigned v) { return __hip_atomic_fetch_add(p, v, __ATOMIC_RELAXED, __HIP_MEMORY_SCOPE_AGENT); }
; #define XB_SPIN(cond, bar) do { unsigned _sp = 0; while (cond) { __builtin_amdgcn_s_sleep(1); \
;     if ((++_sp & 255u) == 0u) { if (xb_ld(&(bar)[XB_TMO])) break; if (_sp > XB_SPIN_CAP) { atomicAdd(&(bar)[XB_TMO], 1u); break; } } } } while (0)
; __device__ __forceinline__ void xcd_barrier(const XcdBarrier& b, bool leader) {
;     ...
;         const unsigned old = xb_add(&bar[XB_XSUB(b.x)], 1u);
;         const unsigned gen = old / nloc;
;         if (old + 1u == (gen + 1u) * nloc) {
;             __builtin_amdgcn_fence(__ATOMIC_RELEASE, "agent");
;             asm volatile("s_waitcnt vmcnt(0)" ::: "memory");
;             const unsigned og = xb_add(&bar[XB_TOP], 1u);
;             const unsigned tg = og / nx;
;             if (og + 1u == (tg + 1u) * nx) xb_add(&bar[XB_TOPGEN], 1u);
;             else XB_SPIN(xb_ld(&bar[XB_TOPGEN]) == tg, bar);
;             __builtin_amdgcn_fence(__ATOMIC_ACQUIRE, "agent");
;             xb_add(&bar[XB_XGEN(b.x)], 1u);
;             asm volatile("s_waitcnt vmcnt(0)" ::: "memory");
;         } else {
;             XB_SPIN(xb_ld(&bar[XB_XGEN(b.x)]) == gen, bar);
;             __builtin_amdgcn_fence(__ATOMIC_ACQUIRE, "agent");
;             asm volatile("s_waitcnt vmcnt(0)" ::: "memory");
;         }
.LBB0_649:
	s_or_b64 exec, exec, s[10:11]
.LBB0_650:
	s_andn2_saveexec_b64 s[8:9], s[8:9]
	s_cbranch_execz .LBB0_670
	s_mov_b64 s[8:9], exec
	buffer_wbl2 sc1
	s_waitcnt lgkmcnt(0)
	s_waitcnt vmcnt(0)
	v_mbcnt_lo_u32_b32 v1, s8, 0
	v_mbcnt_hi_u32_b32 v1, s9, v1
	v_cmp_eq_u32_e32 vcc, 0, v1
	s_and_saveexec_b64 s[10:11], vcc
	s_cbranch_execz .LBB0_653
	s_bcnt1_i32_b64 s8, s[8:9]
	v_mov_b32_e32 v2, 0x3000
	v_mov_b32_e32 v3, s8
	global_atomic_add v2, v2, v3, s[76:77] offset:1024 sc0

; __device__ __forceinline__ unsigned pk2(float lo, float hi) { f32x2_t v = {lo, hi}; bf16x2_t b = __builtin_convertvector(v, bf16x2_t); return __builtin_bit_cast(unsigned, b); }
; __device__ __forceinline__ float rsq_f(float x) { return __builtin_amdgcn_rsqf(x); }
; __device__ __forceinline__ float* karg_out() { return *(volatile KAS fptr_t*)((const KAS char*)__builtin_amdgcn_kernarg_segment_ptr() + 256); }
; __device__ __forceinline__ unsigned char* karg_ws() { return *(volatile KAS ucptr_t*)((const KAS char*)__builtin_amdgcn_kernarg_segment_ptr() + 264); }
; #define lane opq(lane_now())
; template <int MODE>
; __device__ __forceinline__ void sample_norm_rows(const float* gvec, int ish, int gw, int lane) {
;     if (gw >= NS) return;
;     const int row = MPR + gw; float* X = karg_out() + (size_t)row * D;
;     f32x4 v[4]; float s = 0.f;
; #pragma unroll
;     for (int j = 0; j < 4; ++j) { v[j] = *(const f32x4*)(X + 4 * (lane + 64 * j)); s += (v[j][0] * v[j][0] + v[j][1] * v[j][1]) + (v[j][2] * v[j][2] + v[j][3] * v[j][3]); }
;     const float rstd = rsq_f(wave_sum(s) * (1.f / D) + EPS);
;     const float* sh = (const float*)(karg_ws() + WS_ADA) + (size_t)cond_of_row(row) * NADA + ish * D;
; #pragma unroll
;     for (int j = 0; j < 4; ++j) { const int col = 4 * (lane + 64 * j); const f32x4 g = *(const f32x4*)(gvec + col);
;         if (MODE == 0) { const f32x4 y = (v[j] * rstd * g) * (*(const f32x4*)(sh + D + col) + 1.f) + *(const f32x4*)(sh + col);
;             u32x2 o; o.x = pk2(y[0], y[1]); o.y = pk2(y[2], y[3]); *(u32x2*)((bf16*)(karg_ws() + WS_H) + (size_t)row * D + col) = o; }
;         else *(f32x4*)(X + col) = v[j] * rstd * g; }
.LBB0_669:
	s_or_b64 exec, exec, s[10:11]
.LBB0_670:
	s_or_b64 exec, exec, s[4:5]
	s_waitcnt lgkmcnt(0)
	s_barrier
	s_load_dwordx2 s[10:11], s[0:1], 0x68
	s_cmpk_lt_i32 s72, 0x80
	s_cselect_b64 s[4:5], -1, 0
	v_mov_b32_e32 v0, v166
	v_writelane_b32 v238, s4, 8
	s_cmpk_gt_i32 s72, 0x7f
	s_nop 0
	v_writelane_b32 v238, s5, 9
	s_cbranch_scc1 .LBB0_672
	s_load_dwordx2 s[4:5], s[0:1], 0x100
	s_add_i32 s8, s72, 0x4000
	s_ashr_i32 s9, s8, 31
	v_lshlrev_b32_e32 v8, 2, v0
	s_lshl_b64 s[6:7], s[8:9], 12
	s_waitcnt lgkmcnt(0)
	s_add_u32 s4, s4, s6
	v_ashrrev_i32_e32 v9, 31, v8
	s_addc_u32 s5, s5, s7
	v_lshlrev_b64 v[26:27], 2, v[8:9]
	v_lshl_add_u64 v[18:19], s[4:5], 0, v[26:27]
	global_load_dwordx4 v[10:13], v[18:19], off
	global_load_dwordx4 v[14:17], v[18:19], off offset:1024
	global_load_dwordx4 v[0:3], v[18:19], off offset:3072
	global_load_dwordx4 v[4:7], v[18:19], off offset:2048
	s_load_dwordx2 s[4:5], s[0:1], 0x108
	s_ashr_i32 s6, s8, 11
	s_add_i32 s7, s72, 8
	s_cmp_lt_i32 s72, 0
	s_cselect_b32 s6, s6, s7
	s_mul_hi_i32 s7, s6, 0x9000
	s_mul_i32 s6, s6, 0x9000
	s_waitcnt lgkmcnt(0)
	s_add_u32 s6, s4, s6
	s_addc_u32 s7, s5, s7
	s_add_u32 s4, s6, 0x2903000
	s_addc_u32 s5, s7, 0
	s_add_u32 s6, s6, 0x2904000
	s_addc_u32 s7, s7, 0
	v_lshl_add_u64 v[18:19], s[6:7], 0, v[26:27]
	v_lshl_add_u64 v[30:31], s[10:11], 0, v[26:27]
	global_load_dwordx4 v[18:21], v[18:19], off
	v_lshl_add_u64 v[26:27], s[4:5], 0, v[26:27]
	global_load_dwordx4 v[22:25], v[30:31], off
	v_mov_b32_e32 v49, 0x358637bd
	global_load_dwordx4 v[26:29], v[26:27], off
	v_lshlrev_b64 v[34:35], 1, v[8:9]
	s_load_dwordx2 s[10:11], s[0:1], 0x108
	s_lshl_b64 s[8:9], s[8:9], 11
	s_mov_b32 s12, 0x3000000
	v_add_u32_e32 v32, 0x100, v8
	v_ashrrev_i32_e32 v33, 31, v32
	s_waitcnt lgkmcnt(0)
	s_add_u32 s10, s10, s8
	s_addc_u32 s11, s11, s9
	v_lshl_add_u64 v[36:37], s[10:11], 0, v[34:35]
	v_add_co_u32_e32 v36, vcc, s12, v36
	v_lshlrev_b64 v[32:33], 2, v[32:33]
	s_nop 0
	v_addc_co_u32_e32 v37, vcc, 0, v37, vcc
	s_waitcnt vmcnt(6)
	v_pk_mul_f32 v[38:39], v[12:13], v[12:13]
	v_pk_mul_f32 v[40:41], v[10:11], v[10:11]
	s_waitcnt vmcnt(5)
	v_pk_mul_f32 v[42:43], v[16:17], v[16:17]
	v_pk_mul_f32 v[44:45], v[14:15], v[14:15]
	v_pk_mov_b32 v[50:51], v[40:41], v[38:39] op_sel:[1,0]
	v_mov_b32_e32 v41, v39
	v_pk_mov_b32 v[38:39], v[44:45], v[42:43] op_sel:[1,0]
	v_mov_b32_e32 v45, v43
	s_waitcnt vmcnt(3)
	v_mul_f32_e32 v46, v5, v5
	v_mul_f32_e32 v48, v7, v7
	v_pk_add_f32 v[40:41], v[50:51], v[40:41]
	v_pk_add_f32 v[38:39], v[38:39], v[44:45]
	v_mul_f32_e32 v9, v0, v0
	v_mul_f32_e32 v52, v1, v1
	v_mul_f32_e32 v53, v2, v2
	v_mul_f32_e32 v54, v3, v3
	v_pk_fma_f32 v[42:43], v[4:5], v[4:5], v[46:47] op_sel_hi:[1,1,0]
	v_pk_fma_f32 v[46:47], v[6:7], v[6:7], v[48:49] op_sel_hi:[1,1,0]
	v_pk_add_f32 v[40:41], v[40:41], v[40:41] op_sel:[0,1] op_sel_hi:[1,0]
	v_pk_add_f32 v[38:39], v[38:39], v[38:39] op_sel:[0,1] op_sel_hi:[1,0]
	v_mov_b32_e32 v43, v53
	v_mov_b32_e32 v47, v54
	v_mov_b32_e32 v41, v9
	v_mov_b32_e32 v39, v52
	v_pk_add_f32 v[42:43], v[42:43], v[46:47]
	v_pk_add_f32 v[38:39], v[40:41], v[38:39]
	s_waitcnt vmcnt(2)
	v_pk_add_f32 v[20:21], v[20:21], 1.0 op_sel_hi:[1,0]
	v_pk_add_f32 v[38:39], v[38:39], v[42:43]
	v_pk_add_f32 v[18:19], v[18:19], 1.0 op_sel_hi:[1,0]
	v_add_f32_e32 v9, v38, v39
	s_nop 1
	v_add_f32_dpp v9, v9, v9 quad_perm:[1,0,3,2] row_mask:0xf bank_mask:0xf bound_ctrl:1
	s_nop 1
	v_add_f32_dpp v9, v9, v9 quad_perm:[2,3,0,1] row_mask:0xf bank_mask:0xf bound_ctrl:1
	s_nop 1
	v_add_f32_dpp v9, v9, v9 row_half_mirror row_mask:0xf bank_mask:0xf bound_ctrl:1
	s_nop 1
	v_add_f32_dpp v9, v9, v9 row_mirror row_mask:0xf bank_mask:0xf bound_ctrl:1
	s_nop 0
	v_readlane_b32 s13, v9, 16
	v_readlane_b32 s14, v9, 48
	v_readlane_b32 s10, v9, 0
	v_readlane_b32 s11, v9, 32
	v_mov_b32_e32 v38, s13
	v_mov_b32_e32 v39, s14
	v_pk_add_f32 v[38:39], s[10:11], v[38:39]
	s_nop 0
	v_add_f32_e32 v9, v38, v39
	v_fmac_f32_e32 v49, 0x3a800000, v9
	v_rsq_f32_e32 v38, v49
	s_nop 0
	v_pk_mul_f32 v[12:13], v[12:13], v[38:39] op_sel_hi:[1,0]
	v_pk_mul_f32 v[10:11], v[10:11], v[38:39] op_sel_hi:[1,0]
	s_waitcnt vmcnt(1)
; __device__ __forceinline__ unsigned pk2(float lo, float hi) { f32x2_t v = {lo, hi}; bf16x2_t b = __builtin_convertvector(v, bf16x2_t); return __builtin_bit_cast(unsigned, b); }
; __device__ __forceinline__ unsigned char* karg_ws() { return *(volatile KAS ucptr_t*)((const KAS char*)__builtin_amdgcn_kernarg_segment_ptr() + 264); }
; #define lane opq(lane_now())
; template <int MODE>
; __device__ __forceinline__ void sample_norm_rows(const float* gvec, int ish, int gw, int lane) {
;     ...
; #pragma unroll
;     for (int j = 0; j < 4; ++j) { const int col = 4 * (lane + 64 * j); const f32x4 g = *(const f32x4*)(gvec + col);
;         if (MODE == 0) { const f32x4 y = (v[j] * rstd * g) * (*(const f32x4*)(sh + D + col) + 1.f) + *(const f32x4*)(sh + col);
;             u32x2 o; o.x = pk2(y[0], y[1]); o.y = pk2(y[2], y[3]); *(u32x2*)((bf16*)(karg_ws() + WS_H) + (size_t)row * D + col) = o; }
;         else *(f32x4*)(X + col) = v[j] * rstd * g; }
	v_pk_mul_f32 v[12:13], v[24:25], v[12:13]
	v_pk_mul_f32 v[10:11], v[22:23], v[10:11]
	s_waitcnt vmcnt(0)
	v_pk_fma_f32 v[12:13], v[20:21], v[12:13], v[28:29]
	v_pk_fma_f32 v[10:11], v[18:19], v[10:11], v[26:27]
	v_lshl_add_u64 v[18:19], s[6:7], 0, v[32:33]
	v_cvt_pk_bf16_f32 v10, v10, v11
	v_cvt_pk_bf16_f32 v11, v12, v13
	global_store_dwordx2 v[36:37], v[10:11], off
	global_load_dwordx4 v[10:13], v[30:31], off offset:1024
	v_lshl_add_u64 v[22:23], s[4:5], 0, v[32:33]
	global_load_dwordx4 v[18:21], v[18:19], off
	v_pk_mul_f32 v[16:17], v[16:17], v[38:39] op_sel_hi:[1,0]
	global_load_dwordx4 v[22:25], v[22:23], off
	s_load_dwordx2 s[10:11], s[0:1], 0x108
	v_pk_mul_f32 v[14:15], v[14:15], v[38:39] op_sel_hi:[1,0]
	v_add_u32_e32 v26, 0x200, v8
	v_ashrrev_i32_e32 v27, 31, v26
	v_lshlrev_b64 v[26:27], 2, v[26:27]
	s_waitcnt lgkmcnt(0)
	s_add_u32 s10, s10, s8
	s_addc_u32 s11, s11, s9
	v_lshl_add_u64 v[28:29], s[10:11], 0, v[34:35]
	v_add_co_u32_e32 v28, vcc, s12, v28
	v_add_u32_e32 v8, 0x300, v8
	s_nop 0
	v_addc_co_u32_e32 v29, vcc, 0, v29, vcc
	v_ashrrev_i32_e32 v9, 31, v8
	v_pk_mul_f32 v[6:7], v[6:7], v[38:39] op_sel_hi:[1,0]
	v_pk_mul_f32 v[4:5], v[4:5], v[38:39] op_sel_hi:[1,0]
	v_pk_mul_f32 v[2:3], v[2:3], v[38:39] op_sel_hi:[1,0]
	v_pk_mul_f32 v[0:1], v[0:1], v[38:39] op_sel_hi:[1,0]
	s_waitcnt vmcnt(2)
	v_pk_mul_f32 v[10:11], v[10:11], v[14:15]
	v_pk_mul_f32 v[12:13], v[12:13], v[16:17]
	s_waitcnt vmcnt(1)
	v_pk_add_f32 v[14:15], v[20:21], 1.0 op_sel_hi:[1,0]
	v_pk_add_f32 v[16:17], v[18:19], 1.0 op_sel_hi:[1,0]
	s_waitcnt vmcnt(0)
	v_pk_fma_f32 v[12:13], v[14:15], v[12:13], v[24:25]
	v_pk_fma_f32 v[10:11], v[16:17], v[10:11], v[22:23]
	v_lshl_add_u64 v[14:15], s[6:7], 0, v[26:27]
	v_cvt_pk_bf16_f32 v10, v10, v11
	v_cvt_pk_bf16_f32 v11, v12, v13
	global_store_dwordx2 v[28:29], v[10:11], off offset:512
	global_load_dwordx4 v[10:13], v[30:31], off offset:2048
	v_lshl_add_u64 v[18:19], s[4:5], 0, v[26:27]
	global_load_dwordx4 v[14:17], v[14:15], off
	v_lshlrev_b64 v[22:23], 2, v[8:9]
	global_load_dwordx4 v[18:21], v[18:19], off
	s_load_dwordx2 s[10:11], s[0:1], 0x108
	s_waitcnt lgkmcnt(0)
	s_add_u32 s10, s10, s8
	s_addc_u32 s11, s11, s9
	v_lshl_add_u64 v[8:9], s[10:11], 0, v[34:35]
	v_add_co_u32_e32 v8, vcc, s12, v8
	s_waitcnt vmcnt(2)
	v_pk_mul_f32 v[4:5], v[4:5], v[10:11]
	v_pk_mul_f32 v[6:7], v[6:7], v[12:13]
	s_waitcnt vmcnt(1)
	v_pk_add_f32 v[10:11], v[16:17], 1.0 op_sel_hi:[1,0]
	v_pk_add_f32 v[12:13], v[14:15], 1.0 op_sel_hi:[1,0]
	s_waitcnt vmcnt(0)
	v_pk_fma_f32 v[6:7], v[6:7], v[10:11], v[20:21]
	v_pk_fma_f32 v[4:5], v[4:5], v[12:13], v[18:19]
	v_addc_co_u32_e32 v9, vcc, 0, v9, vcc
	v_cvt_pk_bf16_f32 v4, v4, v5
	v_cvt_pk_bf16_f32 v5, v6, v7
	global_store_dwordx2 v[8:9], v[4:5], off offset:1024
	v_lshl_add_u64 v[8:9], s[6:7], 0, v[22:23]
	global_load_dwordx4 v[4:7], v[30:31], off offset:3072
	v_lshl_add_u64 v[12:13], s[4:5], 0, v[22:23]
	global_load_dwordx4 v[8:11], v[8:9], off
	s_waitcnt vmcnt(1)
	v_pk_mul_f32 v[0:1], v[0:1], v[4:5]
	global_load_dwordx4 v[12:15], v[12:13], off
	s_load_dwordx2 s[4:5], s[0:1], 0x108
	v_pk_mul_f32 v[2:3], v[2:3], v[6:7]
	s_waitcnt vmcnt(1)
	v_pk_add_f32 v[4:5], v[10:11], 1.0 op_sel_hi:[1,0]
	v_pk_add_f32 v[6:7], v[8:9], 1.0 op_sel_hi:[1,0]
	s_waitcnt lgkmcnt(0)
	s_add_u32 s4, s4, s8
	s_addc_u32 s5, s5, s9
	v_lshl_add_u64 v[16:17], s[4:5], 0, v[34:35]
	v_add_co_u32_e32 v16, vcc, 0x3000000, v16
	s_waitcnt vmcnt(0)
	v_pk_fma_f32 v[2:3], v[2:3], v[4:5], v[14:15]
	v_pk_fma_f32 v[0:1], v[0:1], v[6:7], v[12:13]
	v_addc_co_u32_e32 v17, vcc, 0, v17, vcc
	v_cvt_pk_bf16_f32 v0, v0, v1
	v_cvt_pk_bf16_f32 v1, v2, v3
	global_store_dwordx2 v[16:17], v[0:1], off offset:1536

; __device__ __forceinline__ unsigned xb_ld(unsigned* p)              { return __hip_atomic_load(p, __ATOMIC_RELAXED, __HIP_MEMORY_SCOPE_AGENT); }
; __device__ __forceinline__ unsigned xb_add(unsigned* p, unsigned v) { return __hip_atomic_fetch_add(p, v, __ATOMIC_RELAXED, __HIP_MEMORY_SCOPE_AGENT); }
; #define XB_SPIN(cond, bar) do { unsigned _sp = 0; while (cond) { __builtin_amdgcn_s_sleep(1); \
;     if ((++_sp & 255u) == 0u) { if (xb_ld(&(bar)[XB_TMO])) break; if (_sp > XB_SPIN_CAP) { atomicAdd(&(bar)[XB_TMO], 1u); break; } } } } while (0)
; __device__ __forceinline__ void xcd_barrier(const XcdBarrier& b, bool leader) {
;     ...
;         const unsigned old = xb_add(&bar[XB_XSUB(b.x)], 1u);
;         const unsigned gen = old / nloc;
;         if (old + 1u == (gen + 1u) * nloc) {
;             __builtin_amdgcn_fence(__ATOMIC_RELEASE, "agent");
;             asm volatile("s_waitcnt vmcnt(0)" ::: "memory");
;             const unsigned og = xb_add(&bar[XB_TOP], 1u);
;             const unsigned tg = og / nx;
;             if (og + 1u == (tg + 1u) * nx) xb_add(&bar[XB_TOPGEN], 1u);
;             else XB_SPIN(xb_ld(&bar[XB_TOPGEN]) == tg, bar);
;             __builtin_amdgcn_fence(__ATOMIC_ACQUIRE, "agent");
;             xb_add(&bar[XB_XGEN(b.x)], 1u);
;             asm volatile("s_waitcnt vmcnt(0)" ::: "memory");
;         } else {
;             XB_SPIN(xb_ld(&bar[XB_XGEN(b.x)]) == gen, bar);
;             __builtin_amdgcn_fence(__ATOMIC_ACQUIRE, "agent");
;             asm volatile("s_waitcnt vmcnt(0)" ::: "memory");
;         }
.LBB0_703:
	s_or_b64 exec, exec, s[10:11]
.LBB0_704:
	s_andn2_saveexec_b64 s[8:9], s[8:9]
	s_cbranch_execz .LBB0_724
	s_mov_b64 s[8:9], exec
	buffer_wbl2 sc1
	s_waitcnt lgkmcnt(0)
	s_waitcnt vmcnt(0)
	v_mbcnt_lo_u32_b32 v1, s8, 0
	v_mbcnt_hi_u32_b32 v1, s9, v1
	v_cmp_eq_u32_e32 vcc, 0, v1
	s_and_saveexec_b64 s[10:11], vcc
	s_cbranch_execz .LBB0_707
	s_bcnt1_i32_b64 s8, s[8:9]
	v_mov_b32_e32 v2, 0x3000
	v_mov_b32_e32 v3, s8
	global_atomic_add v2, v2, v3, s[76:77] offset:1024 sc0

;     __device__ bool next(int i, Unit& u) const { const bool ok = base.next(i >> 1, u); u.sub = i & 1; return ok; }
; __device__ __forceinline__ float* karg_out() { return *(volatile KAS fptr_t*)((const KAS char*)__builtin_amdgcn_kernarg_segment_ptr() + 256); }
;     __device__ bool next(int i, Unit& u) const {
;         const long L = (long)i * G + c; if (L >= nwg) return false;
;         int wgid = (int)L; { const int q = nwg / NXCD, r = nwg % NXCD, xcd = wgid % NXCD, off = wgid / NXCD; wgid = (xcd < r ? xcd * (q + 1) : r * (q + 1) + (xcd - r) * q) + off; }
;         const int nig = WGM * nN, gid = wgid / nig, fm = gid * WGM, gsz = (nM - fm) < WGM ? (nM - fm) : WGM;
;         u.pm = fm + ((wgid % nig) % gsz); u.pn = (wgid % nig) / gsz; u.sub = 0; return true;
; __global__ void __launch_bounds__(NTHR, 2) fwd_megakernel(Params P) {
;     ...
;     { pg8::Gemm g{H, (const bf16*)(ws + WS_WIN), nullptr, nullptr, D}; pg8::StaticOrder S; S.init(MPAD, NIN, G, wg);
;       EpiIn E{Z, MG, (float*)(ws + WS_ABL), karg_out()}; pg8::gemm_phase(lds, g, S, E, wave); }
.LBB0_723:
	s_or_b64 exec, exec, s[10:11]
.LBB0_724:
	s_or_b64 exec, exec, s[4:5]
	s_waitcnt lgkmcnt(0)
	s_barrier
	s_load_dwordx2 s[16:17], s[0:1], 0x100
	s_cmpk_lt_i32 s2, 0x861
	v_mov_b32_e32 v8, v166
	s_cselect_b64 s[4:5], -1, 0
	s_cmpk_gt_i32 s2, 0x860
	s_cbranch_scc1 .LBB0_730
	s_ashr_i32 s6, s2, 31
	s_lshr_b32 s6, s6, 29
	s_add_i32 s8, s2, s6
	s_and_b32 s6, s8, -8
	s_sub_i32 s9, s2, s6
	s_cmp_gt_i32 s9, 0
	s_cbranch_scc0 .LBB0_727
	s_mul_i32 s6, s9, 0x10c
	s_or_b32 s10, s6, 1
	s_cbranch_execz .LBB0_728
	s_branch .LBB0_729

; __device__ __forceinline__ unsigned xb_ld(unsigned* p)              { return __hip_atomic_load(p, __ATOMIC_RELAXED, __HIP_MEMORY_SCOPE_AGENT); }
; __device__ __forceinline__ unsigned xb_add(unsigned* p, unsigned v) { return __hip_atomic_fetch_add(p, v, __ATOMIC_RELAXED, __HIP_MEMORY_SCOPE_AGENT); }
; #define XB_SPIN(cond, bar) do { unsigned _sp = 0; while (cond) { __builtin_amdgcn_s_sleep(1); \
;     if ((++_sp & 255u) == 0u) { if (xb_ld(&(bar)[XB_TMO])) break; if (_sp > XB_SPIN_CAP) { atomicAdd(&(bar)[XB_TMO], 1u); break; } } } } while (0)
; __device__ __forceinline__ void xcd_barrier(const XcdBarrier& b, bool leader) {
;     ...
;         const unsigned old = xb_add(&bar[XB_XSUB(b.x)], 1u);
;         const unsigned gen = old / nloc;
;         if (old + 1u == (gen + 1u) * nloc) {
;             __builtin_amdgcn_fence(__ATOMIC_RELEASE, "agent");
;             asm volatile("s_waitcnt vmcnt(0)" ::: "memory");
;             const unsigned og = xb_add(&bar[XB_TOP], 1u);
;             const unsigned tg = og / nx;
;             if (og + 1u == (tg + 1u) * nx) xb_add(&bar[XB_TOPGEN], 1u);
;             else XB_SPIN(xb_ld(&bar[XB_TOPGEN]) == tg, bar);
;             __builtin_amdgcn_fence(__ATOMIC_ACQUIRE, "agent");
;             xb_add(&bar[XB_XGEN(b.x)], 1u);
;             asm volatile("s_waitcnt vmcnt(0)" ::: "memory");
;         } else {
;             XB_SPIN(xb_ld(&bar[XB_XGEN(b.x)]) == gen, bar);
;             __builtin_amdgcn_fence(__ATOMIC_ACQUIRE, "agent");
;             asm volatile("s_waitcnt vmcnt(0)" ::: "memory");
;         }
.LBB0_1001:
	s_or_b64 exec, exec, s[10:11]
.LBB0_1002:
	s_andn2_saveexec_b64 s[8:9], s[8:9]
	s_cbranch_execz .LBB0_1022
	s_mov_b64 s[8:9], exec
	buffer_wbl2 sc1
	s_waitcnt lgkmcnt(0)
	s_waitcnt vmcnt(0)
	v_mbcnt_lo_u32_b32 v1, s8, 0
	v_mbcnt_hi_u32_b32 v1, s9, v1
	v_cmp_eq_u32_e32 vcc, 0, v1
	s_and_saveexec_b64 s[10:11], vcc
	s_cbranch_execz .LBB0_1005
	s_bcnt1_i32_b64 s8, s[8:9]
	v_mov_b32_e32 v2, 0x3000
	v_mov_b32_e32 v3, s8
	global_atomic_add v2, v2, v3, s[76:77] offset:1024 sc0

; #define LAS __attribute__((address_space(3)))
; #define INP(k) karg_in(k)
; #define lane opq(lane_now())
; #define tid opq((wave << 6) | lane_now())
; __global__ void __launch_bounds__(NTHR, 2) fwd_megakernel(Params P) {
;     ...
;     if constexpr ((PHM >> 7) & 1) {
;         { const int bh0 = (wg * NWAVES) >> 5, h0 = bh0 & 7; LAS float* w = (LAS float*)lds; const float* cwq = INP(22);
;           for (int i = tid; i < 1536; i += NTHR) { const int which = i >> 9, j = (i >> 7) & 3, d = i & 127; w[i] = cwq[(size_t)j * 3072 + which * 1024 + h0 * 128 + d]; }
;           __syncthreads();
;           delta_prep_wave(P, lds, gw, wave, lane);
;           __syncthreads(); }
;         if (G == 256) { const int task = (wg & 7) * 32 + (wg >> 3); rglru_task(P, lds, task >> 5, (task >> 2) & 7, task & 3, tid, 0, RG_SPLIT); }
;         else for (int task = wg; task < 256; task += G) rglru_task(P, lds, task >> 5, (task >> 2) & 7, task & 3, tid, 0, RG_SPLIT);
.LBB0_1021:
	s_or_b64 exec, exec, s[10:11]
.LBB0_1022:
	s_or_b64 exec, exec, s[4:5]
	s_waitcnt lgkmcnt(0)
	s_barrier
	s_mov_b32 s98, 0
	s_cmpk_lg_u32 s78, 0x100
	s_cbranch_scc1 .Lp7a_prep
	s_bitcmp1_b32 s2, 5
	s_cbranch_scc0 .Lp7a_prep
	s_mov_b32 s98, 1
	s_branch .Lp7a_rg

; __device__ __forceinline__ unsigned xb_ld(unsigned* p)              { return __hip_atomic_load(p, __ATOMIC_RELAXED, __HIP_MEMORY_SCOPE_AGENT); }
; __device__ __forceinline__ unsigned xb_add(unsigned* p, unsigned v) { return __hip_atomic_fetch_add(p, v, __ATOMIC_RELAXED, __HIP_MEMORY_SCOPE_AGENT); }
; #define XB_SPIN(cond, bar) do { unsigned _sp = 0; while (cond) { __builtin_amdgcn_s_sleep(1); \
;     if ((++_sp & 255u) == 0u) { if (xb_ld(&(bar)[XB_TMO])) break; if (_sp > XB_SPIN_CAP) { atomicAdd(&(bar)[XB_TMO], 1u); break; } } } } while (0)
; __device__ __forceinline__ void xcd_barrier(const XcdBarrier& b, bool leader) {
;     ...
;         const unsigned old = xb_add(&bar[XB_XSUB(b.x)], 1u);
;         const unsigned gen = old / nloc;
;         if (old + 1u == (gen + 1u) * nloc) {
;             __builtin_amdgcn_fence(__ATOMIC_RELEASE, "agent");
;             asm volatile("s_waitcnt vmcnt(0)" ::: "memory");
;             const unsigned og = xb_add(&bar[XB_TOP], 1u);
;             const unsigned tg = og / nx;
;             if (og + 1u == (tg + 1u) * nx) xb_add(&bar[XB_TOPGEN], 1u);
;             else XB_SPIN(xb_ld(&bar[XB_TOPGEN]) == tg, bar);
;             __builtin_amdgcn_fence(__ATOMIC_ACQUIRE, "agent");
;             xb_add(&bar[XB_XGEN(b.x)], 1u);
;             asm volatile("s_waitcnt vmcnt(0)" ::: "memory");
;         } else {
;             XB_SPIN(xb_ld(&bar[XB_XGEN(b.x)]) == gen, bar);
.LBB0_1428:
	s_or_b64 exec, exec, s[10:11]
	v_cvt_f32_u32_e32 v4, v2
	s_waitcnt vmcnt(0)
	v_readfirstlane_b32 s3, v3
	v_sub_u32_e32 v3, 0, v2
	v_rcp_iflag_f32_e32 v4, v4
	v_add_u32_e32 v5, s3, v1
	v_mul_f32_e32 v4, 0x4f7ffffe, v4
	v_cvt_u32_f32_e32 v4, v4
	v_mul_lo_u32 v1, v3, v4
	v_mul_hi_u32 v1, v4, v1
	v_add_u32_e32 v1, v4, v1
	v_mul_hi_u32 v1, v5, v1
	v_mul_lo_u32 v3, v1, v2
	v_sub_u32_e32 v3, v5, v3
	v_add_u32_e32 v4, 1, v1
	v_cmp_ge_u32_e32 vcc, v3, v2
	s_nop 1
	v_cndmask_b32_e32 v1, v1, v4, vcc
	v_sub_u32_e32 v4, v3, v2
	v_cndmask_b32_e32 v3, v3, v4, vcc
	v_add_u32_e32 v4, 1, v1
	v_cmp_ge_u32_e32 vcc, v3, v2
	v_add_u32_e32 v3, 1, v5
	s_nop 0
	v_cndmask_b32_e32 v1, v1, v4, vcc
	v_mul_lo_u32 v4, v2, v1
	v_add_u32_e32 v2, v4, v2
	v_cmp_ne_u32_e32 vcc, v3, v2
	s_and_saveexec_b64 s[8:9], vcc
	s_xor_b64 s[8:9], exec, s[8:9]
	s_cbranch_execz .LBB0_1446
	buffer_inv sc1
	s_waitcnt lgkmcnt(0)
	v_add_u32_e32 v1, 1, v1
	v_mul_lo_u32 v1, v1, v0
	v_mov_b32_e32 v0, 0x3000
	global_load_dword v0, v0, s[76:77] offset:1024 sc1
	s_add_u32 s12, s76, 0x3400
	s_addc_u32 s13, s77, 0
	s_waitcnt vmcnt(0)
	v_cmp_lt_u32_e32 vcc, v0, v1
	s_and_saveexec_b64 s[10:11], vcc
	s_cbranch_execz .LBB0_1445
	s_mov_b32 s3, 1
	s_mov_b64 s[14:15], 0
	v_mov_b32_e32 v239, v0
	v_mov_b32_e32 v0, 0
	s_branch .LBB0_1432

; __device__ __forceinline__ unsigned xb_ld(unsigned* p)              { return __hip_atomic_load(p, __ATOMIC_RELAXED, __HIP_MEMORY_SCOPE_AGENT); }
; #define XB_SPIN(cond, bar) do { unsigned _sp = 0; while (cond) { __builtin_amdgcn_s_sleep(1); \
;     if ((++_sp & 255u) == 0u) { if (xb_ld(&(bar)[XB_TMO])) break; if (_sp > XB_SPIN_CAP) { atomicAdd(&(bar)[XB_TMO], 1u); break; } } } } while (0)
; __device__ __forceinline__ void xcd_barrier(const XcdBarrier& b, bool leader) {
;     ...
;         } else {
;             XB_SPIN(xb_ld(&bar[XB_XGEN(b.x)]) == gen, bar);
.LBB0_1436:
	global_load_dword v239, v0, s[12:13] sc1
	s_add_i32 s3, s3, 1
	s_mov_b64 s[20:21], -1
	s_waitcnt vmcnt(1)
	v_cmp_ge_u32_e32 vcc, v239, v1
	s_orn2_b64 s[18:19], vcc, exec
	s_branch .LBB0_1431

; __device__ __forceinline__ unsigned xb_ld(unsigned* p)              { return __hip_atomic_load(p, __ATOMIC_RELAXED, __HIP_MEMORY_SCOPE_AGENT); }
; __device__ __forceinline__ unsigned xb_add(unsigned* p, unsigned v) { return __hip_atomic_fetch_add(p, v, __ATOMIC_RELAXED, __HIP_MEMORY_SCOPE_AGENT); }
; #define XB_SPIN(cond, bar) do { unsigned _sp = 0; while (cond) { __builtin_amdgcn_s_sleep(1); \
;     if ((++_sp & 255u) == 0u) { if (xb_ld(&(bar)[XB_TMO])) break; if (_sp > XB_SPIN_CAP) { atomicAdd(&(bar)[XB_TMO], 1u); break; } } } } while (0)
; __device__ __forceinline__ void xcd_barrier(const XcdBarrier& b, bool leader) {
;     ...
;         const unsigned old = xb_add(&bar[XB_XSUB(b.x)], 1u);
;         const unsigned gen = old / nloc;
;         if (old + 1u == (gen + 1u) * nloc) {
;             __builtin_amdgcn_fence(__ATOMIC_RELEASE, "agent");
;             asm volatile("s_waitcnt vmcnt(0)" ::: "memory");
;             const unsigned og = xb_add(&bar[XB_TOP], 1u);
;             const unsigned tg = og / nx;
;             if (og + 1u == (tg + 1u) * nx) xb_add(&bar[XB_TOPGEN], 1u);
;             else XB_SPIN(xb_ld(&bar[XB_TOPGEN]) == tg, bar);
;             __builtin_amdgcn_fence(__ATOMIC_ACQUIRE, "agent");
;             xb_add(&bar[XB_XGEN(b.x)], 1u);
;             asm volatile("s_waitcnt vmcnt(0)" ::: "memory");
;         } else {
;             XB_SPIN(xb_ld(&bar[XB_XGEN(b.x)]) == gen, bar);
;             __builtin_amdgcn_fence(__ATOMIC_ACQUIRE, "agent");
;             asm volatile("s_waitcnt vmcnt(0)" ::: "memory");
;         }
.LBB0_1445:
	s_or_b64 exec, exec, s[10:11]
.LBB0_1446:
	s_andn2_saveexec_b64 s[8:9], s[8:9]
	s_cbranch_execz .LBB0_1466
	s_mov_b64 s[8:9], exec
	buffer_wbl2 sc1
	s_waitcnt lgkmcnt(0)
	s_waitcnt vmcnt(0)
	v_mbcnt_lo_u32_b32 v1, s8, 0
	v_mbcnt_hi_u32_b32 v1, s9, v1
	v_cmp_eq_u32_e32 vcc, 0, v1
	s_and_saveexec_b64 s[10:11], vcc
	s_cbranch_execz .LBB0_1449
	s_bcnt1_i32_b64 s3, s[8:9]
	v_mov_b32_e32 v2, 0x3000
	v_mov_b32_e32 v3, s3
	global_atomic_add v2, v2, v3, s[76:77] offset:1024 sc0
.LBB0_1449:
	s_or_b64 exec, exec, s[10:11]
	buffer_inv sc1
	v_cvt_f32_u32_e32 v3, v0
	s_waitcnt vmcnt(0)
	v_readfirstlane_b32 s3, v2
	s_add_u32 s10, s76, 0x3500
	s_addc_u32 s11, s77, 0
	v_rcp_iflag_f32_e32 v3, v3
	v_add_u32_e32 v1, s3, v1
	v_add_u32_e32 v4, 1, v1
	s_mov_b64 s[12:13], -1
	v_mul_f32_e32 v2, 0x4f7ffffe, v3
	v_cvt_u32_f32_e32 v2, v2
	v_sub_u32_e32 v3, 0, v0
	v_mul_lo_u32 v3, v3, v2
	v_mul_hi_u32 v3, v2, v3
	v_add_u32_e32 v2, v2, v3
	v_mul_hi_u32 v2, v1, v2
	v_mul_lo_u32 v3, v2, v0
	v_sub_u32_e32 v1, v1, v3
	v_add_u32_e32 v5, 1, v2
	v_cmp_ge_u32_e32 vcc, v1, v0
	v_sub_u32_e32 v3, v1, v0
	s_nop 0
	v_cndmask_b32_e32 v2, v2, v5, vcc
	v_cndmask_b32_e32 v1, v1, v3, vcc
	v_add_u32_e32 v3, 1, v2
	v_cmp_ge_u32_e32 vcc, v1, v0
	s_nop 1
	v_cndmask_b32_e32 v2, v2, v3, vcc
	v_mul_lo_u32 v1, v0, v2
	v_add_u32_e32 v0, v1, v0
	v_mov_b32_e32 v2, v0
	v_cmp_ne_u32_e32 vcc, v4, v0
	v_mov_b64_e32 v[0:1], s[10:11]
	s_and_saveexec_b64 s[8:9], vcc
	s_cbranch_execz .LBB0_1461
	v_mov_b32_e32 v0, 0
	global_load_dword v1, v0, s[10:11] offset:-256 sc1
	s_mov_b64 s[16:17], 0
	s_waitcnt vmcnt(0)
	v_cmp_lt_u32_e32 vcc, v1, v2
	s_and_saveexec_b64 s[14:15], vcc
	s_cbranch_execz .LBB0_1460
	v_mov_b32_e32 v239, v1
	s_add_u32 s12, s76, 0x200
	s_addc_u32 s13, s77, 0
	s_mov_b32 s3, 1
	s_branch .LBB0_1453

; __device__ __forceinline__ unsigned xb_ld(unsigned* p)              { return __hip_atomic_load(p, __ATOMIC_RELAXED, __HIP_MEMORY_SCOPE_AGENT); }
; __device__ __forceinline__ unsigned xb_add(unsigned* p, unsigned v) { return __hip_atomic_fetch_add(p, v, __ATOMIC_RELAXED, __HIP_MEMORY_SCOPE_AGENT); }
; #define XB_SPIN(cond, bar) do { unsigned _sp = 0; while (cond) { __builtin_amdgcn_s_sleep(1); \
;     if ((++_sp & 255u) == 0u) { if (xb_ld(&(bar)[XB_TMO])) break; if (_sp > XB_SPIN_CAP) { atomicAdd(&(bar)[XB_TMO], 1u); break; } } } } while (0)
; __device__ __forceinline__ void xcd_barrier(const XcdBarrier& b, bool leader) {
;     ...
;             const unsigned og = xb_add(&bar[XB_TOP], 1u);
;             const unsigned tg = og / nx;
;             if (og + 1u == (tg + 1u) * nx) xb_add(&bar[XB_TOPGEN], 1u);
;             else XB_SPIN(xb_ld(&bar[XB_TOPGEN]) == tg, bar);
.LBB0_1457:
	global_load_dword v239, v0, s[10:11] offset:-256 sc1
	s_add_i32 s3, s3, 1
	s_mov_b64 s[20:21], -1
	s_waitcnt vmcnt(1)
	v_cmp_ge_u32_e32 vcc, v239, v2
	s_orn2_b64 s[24:25], vcc, exec
	s_branch .LBB0_1452

; #define LAS __attribute__((address_space(3)))
; __device__ __forceinline__ float softplus_f(float x) { return x > 20.f ? x : log1pf(__expf(x)); }
; #define INP(k) karg_in(k)
; __device__ __forceinline__ void rglru_task(const Params& P, LAS unsigned char* lds, int b, int n, int qd, int tid, int t0, int t1) {
;     const int lane = tid & 63, wave = tid >> 6;
;     LAS bf16* xcA = (LAS bf16*)lds;
;     LAS float* xcf = (LAS float*)(lds + 34816);
;     LAS float* rb = (LAS float*)(lds + 51200);
;     LAS float* ib = (LAS float*)(lds + 67584);
;     LAS float* segA = (LAS float*)(lds + 83968);
;     LAS float* segB = (LAS float*)(lds + 86016);
;     LAS float* hc = (LAS float*)(lds + 88064);
;     LAS float* cw = (LAS float*)(lds + 88192);
;     LAS bf16* rawt = (LAS bf16*)(lds + 90752);
;     bf16* XR = (bf16*)(karg_ws() + WS_Z); bf16* GR = (bf16*)(karg_ws() + WS_Z + ZB);
;     const bf16* WRG = (const bf16*)(karg_ws() + WS_WRG);
;     const int cb0 = n * 128, oc0 = cb0 + qd * 32;
;     const bool prompt = b >= 0;
;     for (int i = tid; i < 640; i += NTHR) cw[i] = i < 512 ? INP(15)[(size_t)(i >> 7) * D + cb0 + (i & 127)] : INP(16)[cb0 + (i - 512)];
;     if (tid < 32) hc[tid] = t0 > 0 ? ((const float*)(karg_ws() + WS_HCARRY))[(size_t)b * D + oc0 + tid] : 0.f;
;     const int tb = wave & 3, cbk = wave >> 2;
;     bf16x8 Bf[8];
;     { const bf16* wrow = WRG + (size_t)(n * 256 + cbk * 128 + qd * 32 + (lane & 31)) * 128 + (lane >> 5) * 8;
; #pragma unroll
;       for (int ks = 0; ks < 8; ++ks) Bf[ks] = *(const bf16x8*)(wrow + ks * 16); }
;     const float gbias = INP(cbk ? 20 : 18)[oc0 + (lane & 31)];
;     const int ch = tid & 31, seg = tid >> 5;
;     const float sp = softplus_f(-INP(21)[oc0 + ch]);
; __global__ void __launch_bounds__(NTHR, 2) fwd_megakernel(Params P) {
;     ...
;         if (wg < 64) delta_rec_task(P, lds, wg >> 3, wg & 7, tid);
;         else {
;             if (G == 256) { const int slot = (wg - 64) >> 3;
;                 { const int task = (wg & 7) * 32 + slot; rglru_task(P, lds, task >> 5, (task >> 2) & 7, task & 3, tid, RG_SPLIT, 16); }
;                 if (slot < 8) { const int task = (wg & 7) * 32 + 24 + slot; rglru_task(P, lds, task >> 5, (task >> 2) & 7, task & 3, tid, RG_SPLIT, 16); } }
;             else for (int task = wg - 64; task < 256; task += G - 64) rglru_task(P, lds, task >> 5, (task >> 2) & 7, task & 3, tid, RG_SPLIT, 16);
.LBB0_1463:
	s_or_b64 exec, exec, s[8:9]
	s_mov_b64 s[8:9], exec
	v_mbcnt_lo_u32_b32 v0, s8, 0
	v_mbcnt_hi_u32_b32 v0, s9, v0
	v_cmp_eq_u32_e32 vcc, 0, v0
	s_and_saveexec_b64 s[10:11], vcc
	s_cbranch_execz .LBB0_1465
	s_bcnt1_i32_b64 s3, s[8:9]
	v_mov_b32_e32 v0, 0x2000
	v_mov_b32_e32 v1, s3
.LBB0_1465:
	s_or_b64 exec, exec, s[10:11]
.LBB0_1466:
	s_or_b64 exec, exec, s[4:5]
	s_cmp_gt_i32 s2, 63
	s_mov_b64 s[4:5], -1
	s_waitcnt lgkmcnt(0)
	s_barrier
	s_cbranch_scc0 .LBB0_1811
	v_readlane_b32 s6, v238, 21
	v_readlane_b32 s7, v238, 22
	s_and_b64 vcc, exec, s[6:7]
	s_cbranch_vccz .LBB0_1622
	s_cmpk_gt_u32 s2, 0x13f
	s_cbranch_scc1 .LBB0_1621
	s_sub_i32 s3, s2, 64
	s_sub_i32 s68, s78, 64
	s_mov_b32 s55, 0
	v_mov_b32_e32 v16, 0
	s_add_i32 s4, 0, 0x15880
	v_mov_b32_e32 v75, 0xa0
	v_mov_b32_e32 v150, 0x90
	v_mov_b32_e32 v151, 0x3ecc95a3
	s_movk_i32 s70, 0x830
	s_movk_i32 s71, 0xfc82
	s_movk_i32 s72, 0x630
	s_movk_i32 s73, 0x430
	s_movk_i32 s83, 0x230
	s_add_i32 s88, 0, 0x16280
	s_movk_i32 s89, 0x110
	s_add_i32 s90, 0, 0xc800
	s_add_i32 s91, 0, 0x10800
	s_add_i32 s94, 0, 0x14800
	s_add_i32 s95, 0, 0x15000
	s_movk_i32 s96, 0xc00
	s_movk_i32 s97, 0x1000
	v_mov_b32_e32 v152, 0x3c088889
	s_mov_b32 s60, 0xbe99999a
	v_mov_b32_e32 v72, 0x3f317218
	v_mov_b32_e32 v153, 0x7f800000
	v_mov_b32_e32 v154, 0x7fc00000
	v_mov_b32_e32 v155, 0xff800000
	v_mov_b32_e32 v156, 0x8800
	v_writelane_b32 v238, s4, 21
	s_branch .LBB0_1471

; __device__ __forceinline__ unsigned xb_ld(unsigned* p)              { return __hip_atomic_load(p, __ATOMIC_RELAXED, __HIP_MEMORY_SCOPE_AGENT); }
; __device__ __forceinline__ unsigned xb_add(unsigned* p, unsigned v) { return __hip_atomic_fetch_add(p, v, __ATOMIC_RELAXED, __HIP_MEMORY_SCOPE_AGENT); }
; #define XB_SPIN(cond, bar) do { unsigned _sp = 0; while (cond) { __builtin_amdgcn_s_sleep(1); \
;     if ((++_sp & 255u) == 0u) { if (xb_ld(&(bar)[XB_TMO])) break; if (_sp > XB_SPIN_CAP) { atomicAdd(&(bar)[XB_TMO], 1u); break; } } } } while (0)
; __device__ __forceinline__ void xcd_barrier(const XcdBarrier& b, bool leader) {
;     ...
;         const unsigned old = xb_add(&bar[XB_XSUB(b.x)], 1u);
;         const unsigned gen = old / nloc;
;         if (old + 1u == (gen + 1u) * nloc) {
;             __builtin_amdgcn_fence(__ATOMIC_RELEASE, "agent");
;             asm volatile("s_waitcnt vmcnt(0)" ::: "memory");
;             const unsigned og = xb_add(&bar[XB_TOP], 1u);
;             const unsigned tg = og / nx;
;             if (og + 1u == (tg + 1u) * nx) xb_add(&bar[XB_TOPGEN], 1u);
;             else XB_SPIN(xb_ld(&bar[XB_TOPGEN]) == tg, bar);
;             __builtin_amdgcn_fence(__ATOMIC_ACQUIRE, "agent");
;             xb_add(&bar[XB_XGEN(b.x)], 1u);
;             asm volatile("s_waitcnt vmcnt(0)" ::: "memory");
;         } else {
;             XB_SPIN(xb_ld(&bar[XB_XGEN(b.x)]) == gen, bar);
;             __builtin_amdgcn_fence(__ATOMIC_ACQUIRE, "agent");
;             asm volatile("s_waitcnt vmcnt(0)" ::: "memory");
;         }
.LBB0_1865:
	s_or_b64 exec, exec, s[10:11]
.LBB0_1866:
	s_andn2_saveexec_b64 s[8:9], s[8:9]
	s_cbranch_execz .LBB0_1890
	s_mov_b64 s[8:9], exec
	buffer_wbl2 sc1
	s_waitcnt lgkmcnt(0)
	s_waitcnt vmcnt(0)
	v_mbcnt_lo_u32_b32 v1, s8, 0
	v_mbcnt_hi_u32_b32 v1, s9, v1
	v_cmp_eq_u32_e32 vcc, 0, v1
	s_and_saveexec_b64 s[10:11], vcc
	s_cbranch_execz .LBB0_1869
	s_bcnt1_i32_b64 s3, s[8:9]
	v_mov_b32_e32 v2, 0x3000
	v_mov_b32_e32 v3, s3
	global_atomic_add v2, v2, v3, s[76:77] offset:1024 sc0

;     __device__ bool next(int i, Unit& u) const {
;         const long L = (long)i * G + c; if (L >= nwg) return false;
;         int wgid = (int)L; { const int q = nwg / NXCD, r = nwg % NXCD, xcd = wgid % NXCD, off = wgid / NXCD; wgid = (xcd < r ? xcd * (q + 1) : r * (q + 1) + (xcd - r) * q) + off; }
;         const int nig = WGM * nN, gid = wgid / nig, fm = gid * WGM, gsz = (nM - fm) < WGM ? (nM - fm) : WGM;
;         u.pm = fm + ((wgid % nig) % gsz); u.pn = (wgid % nig) / gsz; u.sub = 0; return true;
;     }
;     __device__ bool next(int i, Unit& u) const { const bool ok = base.next(i >> 1, u); u.sub = i & 1; return ok; }
; __global__ void __launch_bounds__(NTHR, 2) fwd_megakernel(Params P) {
;     ...
;     { pg8::Gemm g{Z + 1 * (ZB / 2), (const bf16*)(ws + WS_WBR), Z + 5 * (ZB / 2), (const bf16*)(ws + WS_WBR) + (size_t)D * D, D};
;       pg8::PairOrder S; S.base.init(MPR, D, G, wg);
;       EpiBranch E{MG, MG + ZB / 2, Z}; pg8::gemm_phase(lds, g, S, E, wave);
.LBB0_1889:
	s_or_b64 exec, exec, s[10:11]
.LBB0_1890:
	s_or_b64 exec, exec, s[4:5]
	v_readlane_b32 s4, v238, 10
	v_readlane_b32 s5, v238, 11
	v_mov_b32_e32 v1, v166
	s_and_b64 vcc, exec, s[4:5]
	s_waitcnt lgkmcnt(0)
	s_barrier
	s_cbranch_vccnz .LBB0_1896
	s_ashr_i32 s3, s2, 31
	s_lshr_b32 s3, s3, 29
	s_add_i32 s3, s2, s3
	s_and_b32 s4, s3, -8
	s_sub_i32 s6, s2, s4
	s_cmp_gt_i32 s6, -1
	s_cbranch_scc0 .LBB0_1893
	s_lshl_b32 s7, s6, 5
	s_cbranch_execz .LBB0_1894
	s_branch .LBB0_1895

; __device__ __forceinline__ unsigned xb_ld(unsigned* p)              { return __hip_atomic_load(p, __ATOMIC_RELAXED, __HIP_MEMORY_SCOPE_AGENT); }
; __device__ __forceinline__ unsigned xb_add(unsigned* p, unsigned v) { return __hip_atomic_fetch_add(p, v, __ATOMIC_RELAXED, __HIP_MEMORY_SCOPE_AGENT); }
; #define XB_SPIN(cond, bar) do { unsigned _sp = 0; while (cond) { __builtin_amdgcn_s_sleep(1); \
;     if ((++_sp & 255u) == 0u) { if (xb_ld(&(bar)[XB_TMO])) break; if (_sp > XB_SPIN_CAP) { atomicAdd(&(bar)[XB_TMO], 1u); break; } } } } while (0)
; __device__ __forceinline__ void xcd_barrier(const XcdBarrier& b, bool leader) {
;     ...
;         const unsigned old = xb_add(&bar[XB_XSUB(b.x)], 1u);
;         const unsigned gen = old / nloc;
;         if (old + 1u == (gen + 1u) * nloc) {
;             __builtin_amdgcn_fence(__ATOMIC_RELEASE, "agent");
;             asm volatile("s_waitcnt vmcnt(0)" ::: "memory");
;             const unsigned og = xb_add(&bar[XB_TOP], 1u);
;             const unsigned tg = og / nx;
;             if (og + 1u == (tg + 1u) * nx) xb_add(&bar[XB_TOPGEN], 1u);
;             else XB_SPIN(xb_ld(&bar[XB_TOPGEN]) == tg, bar);
;             __builtin_amdgcn_fence(__ATOMIC_ACQUIRE, "agent");
;             xb_add(&bar[XB_XGEN(b.x)], 1u);
;             asm volatile("s_waitcnt vmcnt(0)" ::: "memory");
;         } else {
;             XB_SPIN(xb_ld(&bar[XB_XGEN(b.x)]) == gen, bar);
;             __builtin_amdgcn_fence(__ATOMIC_ACQUIRE, "agent");
;             asm volatile("s_waitcnt vmcnt(0)" ::: "memory");
;         }
.LBB0_1974:
	s_or_b64 exec, exec, s[10:11]
.LBB0_1975:
	s_andn2_saveexec_b64 s[8:9], s[8:9]
	s_cbranch_execz .LBB0_1995
	s_mov_b64 s[8:9], exec
	buffer_wbl2 sc1
	s_waitcnt lgkmcnt(0)
	s_waitcnt vmcnt(0)
	v_mbcnt_lo_u32_b32 v1, s8, 0
	v_mbcnt_hi_u32_b32 v1, s9, v1
	v_cmp_eq_u32_e32 vcc, 0, v1
	s_and_saveexec_b64 s[10:11], vcc
	s_cbranch_execz .LBB0_1978
	s_bcnt1_i32_b64 s3, s[8:9]
	v_mov_b32_e32 v2, 0x3000
	v_mov_b32_e32 v3, s3
	global_atomic_add v2, v2, v3, s[76:77] offset:1024 sc0

; #define LAS __attribute__((address_space(3)))
;     __device__ bool next(int i, Unit& u) const { const bool ok = base.next(i >> 1, u); u.sub = i & 1; return ok; }
; __device__ __forceinline__ float* karg_out() { return *(volatile KAS fptr_t*)((const KAS char*)__builtin_amdgcn_kernarg_segment_ptr() + 256); }
; #define INP(k) karg_in(k)
;     __device__ bool next(int i, Unit& u) const {
;         const long L = (long)i * G + c; if (L >= nwg) return false;
;         int wgid = (int)L; { const int q = nwg / NXCD, r = nwg % NXCD, xcd = wgid % NXCD, off = wgid / NXCD; wgid = (xcd < r ? xcd * (q + 1) : r * (q + 1) + (xcd - r) * q) + off; }
;         const int nig = WGM * nN, gid = wgid / nig, fm = gid * WGM, gsz = (nM - fm) < WGM ? (nM - fm) : WGM;
;         u.pm = fm + ((wgid % nig) % gsz); u.pn = (wgid % nig) / gsz; u.sub = 0; return true;
; __global__ void __launch_bounds__(NTHR, 2) fwd_megakernel(Params P) {
;     ...
;     { pg8::Gemm g{Z, (const bf16*)(ws + WS_WOUT), nullptr, nullptr, D}; pg8::StaticOrder S; S.init(MPR, D, G, wg);
;       EpiResidNorm<0> E{karg_out(), nullptr, ADA + 5 * D, 1.0f, INP(28), ADA + 6 * D, H, (float*)(ws + WS_PART) + 65536, (unsigned*)(ws + WS_CNT) + 64, (LAS float*)(lds + 131072)}; pg8::gemm_phase(lds, g, S, E, wave);
.LBB0_1994:
	s_or_b64 exec, exec, s[10:11]
.LBB0_1995:
	s_or_b64 exec, exec, s[4:5]
	s_waitcnt lgkmcnt(0)
	s_barrier
	s_load_dwordx2 s[14:15], s[0:1], 0x100
	s_load_dwordx2 s[16:17], s[0:1], 0xe0
	v_mov_b32_e32 v8, v166
	s_and_b64 vcc, exec, s[90:91]
	s_cbranch_vccnz .LBB0_2001
	s_ashr_i32 s3, s2, 31
	s_lshr_b32 s3, s3, 29
	s_add_i32 s3, s2, s3
	s_and_b32 s4, s3, -8
	s_sub_i32 s6, s2, s4
	s_cmp_gt_i32 s6, -1
	s_cbranch_scc0 .LBB0_1998
	s_lshl_b32 s7, s6, 5
	s_cbranch_execz .LBB0_1999
	s_branch .LBB0_2000

; __device__ __forceinline__ unsigned xb_ld(unsigned* p)              { return __hip_atomic_load(p, __ATOMIC_RELAXED, __HIP_MEMORY_SCOPE_AGENT); }
; __device__ __forceinline__ unsigned xb_add(unsigned* p, unsigned v) { return __hip_atomic_fetch_add(p, v, __ATOMIC_RELAXED, __HIP_MEMORY_SCOPE_AGENT); }
; #define XB_SPIN(cond, bar) do { unsigned _sp = 0; while (cond) { __builtin_amdgcn_s_sleep(1); \
;     if ((++_sp & 255u) == 0u) { if (xb_ld(&(bar)[XB_TMO])) break; if (_sp > XB_SPIN_CAP) { atomicAdd(&(bar)[XB_TMO], 1u); break; } } } } while (0)
; __device__ __forceinline__ void xcd_barrier(const XcdBarrier& b, bool leader) {
;     ...
;         const unsigned old = xb_add(&bar[XB_XSUB(b.x)], 1u);
;         const unsigned gen = old / nloc;
;         if (old + 1u == (gen + 1u) * nloc) {
;             __builtin_amdgcn_fence(__ATOMIC_RELEASE, "agent");
;             asm volatile("s_waitcnt vmcnt(0)" ::: "memory");
;             const unsigned og = xb_add(&bar[XB_TOP], 1u);
;             const unsigned tg = og / nx;
;             if (og + 1u == (tg + 1u) * nx) xb_add(&bar[XB_TOPGEN], 1u);
;             else XB_SPIN(xb_ld(&bar[XB_TOPGEN]) == tg, bar);
;             __builtin_amdgcn_fence(__ATOMIC_ACQUIRE, "agent");
;             xb_add(&bar[XB_XGEN(b.x)], 1u);
;             asm volatile("s_waitcnt vmcnt(0)" ::: "memory");
;         } else {
;             XB_SPIN(xb_ld(&bar[XB_XGEN(b.x)]) == gen, bar);
;             __builtin_amdgcn_fence(__ATOMIC_ACQUIRE, "agent");
;             asm volatile("s_waitcnt vmcnt(0)" ::: "memory");
;         }
.LBB0_2080:
	s_or_b64 exec, exec, s[10:11]
.LBB0_2081:
	s_andn2_saveexec_b64 s[8:9], s[8:9]
	s_cbranch_execz .LBB0_2101
	s_mov_b64 s[8:9], exec
	buffer_wbl2 sc1
	s_waitcnt lgkmcnt(0)
	s_waitcnt vmcnt(0)
	v_mbcnt_lo_u32_b32 v1, s8, 0
	v_mbcnt_hi_u32_b32 v1, s9, v1
	v_cmp_eq_u32_e32 vcc, 0, v1
	s_and_saveexec_b64 s[10:11], vcc
	s_cbranch_execz .LBB0_2084
	s_bcnt1_i32_b64 s3, s[8:9]
	v_mov_b32_e32 v2, 0x3000
	v_mov_b32_e32 v3, s3
	global_atomic_add v2, v2, v3, s[76:77] offset:1024 sc0

; __device__ __forceinline__ unsigned pk2(float lo, float hi) { f32x2_t v = {lo, hi}; bf16x2_t b = __builtin_convertvector(v, bf16x2_t); return __builtin_bit_cast(unsigned, b); }
; __device__ __forceinline__ float rsq_f(float x) { return __builtin_amdgcn_rsqf(x); }
; __device__ __forceinline__ float* karg_out() { return *(volatile KAS fptr_t*)((const KAS char*)__builtin_amdgcn_kernarg_segment_ptr() + 256); }
; __device__ __forceinline__ unsigned char* karg_ws() { return *(volatile KAS ucptr_t*)((const KAS char*)__builtin_amdgcn_kernarg_segment_ptr() + 264); }
; #define INP(k) karg_in(k)
; #define lane opq(lane_now())
; template <int MODE>
; __device__ __forceinline__ void sample_norm_rows(const float* gvec, int ish, int gw, int lane) {
;     if (gw >= NS) return;
;     const int row = MPR + gw; float* X = karg_out() + (size_t)row * D;
;     f32x4 v[4]; float s = 0.f;
; #pragma unroll
;     for (int j = 0; j < 4; ++j) { v[j] = *(const f32x4*)(X + 4 * (lane + 64 * j)); s += (v[j][0] * v[j][0] + v[j][1] * v[j][1]) + (v[j][2] * v[j][2] + v[j][3] * v[j][3]); }
;     const float rstd = rsq_f(wave_sum(s) * (1.f / D) + EPS);
;     const float* sh = (const float*)(karg_ws() + WS_ADA) + (size_t)cond_of_row(row) * NADA + ish * D;
; #pragma unroll
;     for (int j = 0; j < 4; ++j) { const int col = 4 * (lane + 64 * j); const f32x4 g = *(const f32x4*)(gvec + col);
;         if (MODE == 0) { const f32x4 y = (v[j] * rstd * g) * (*(const f32x4*)(sh + D + col) + 1.f) + *(const f32x4*)(sh + col);
;             u32x2 o; o.x = pk2(y[0], y[1]); o.y = pk2(y[2], y[3]); *(u32x2*)((bf16*)(karg_ws() + WS_H) + (size_t)row * D + col) = o; }
;         else *(f32x4*)(X + col) = v[j] * rstd * g; }
; __global__ void __launch_bounds__(NTHR, 2) fwd_megakernel(Params P) {
;     ...
;     sample_norm_rows<0>(INP(28), 6, gw, lane);
.LBB0_2100:
	s_or_b64 exec, exec, s[10:11]
.LBB0_2101:
	s_or_b64 exec, exec, s[4:5]
	s_waitcnt lgkmcnt(0)
	s_barrier
	s_load_dwordx2 s[12:13], s[0:1], 0xe0
	v_readlane_b32 s4, v238, 8
	v_readlane_b32 s5, v238, 9
	v_mov_b32_e32 v0, v166
	s_andn2_b64 vcc, exec, s[4:5]
	v_cndmask_b32_e64 v1, 0, 1, s[4:5]
	v_cmp_ne_u32_e64 s[8:9], 1, v1
	s_cbranch_vccnz .LBB0_2103
	s_load_dwordx2 s[4:5], s[0:1], 0x100
	s_add_i32 s10, s70, 0x4000
	s_ashr_i32 s11, s10, 31
	v_lshlrev_b32_e32 v8, 2, v0
	s_lshl_b64 s[6:7], s[10:11], 12
	s_waitcnt lgkmcnt(0)
	s_add_u32 s4, s4, s6
	v_ashrrev_i32_e32 v9, 31, v8
	s_addc_u32 s5, s5, s7
	v_lshlrev_b64 v[26:27], 2, v[8:9]
	v_lshl_add_u64 v[18:19], s[4:5], 0, v[26:27]
	global_load_dwordx4 v[10:13], v[18:19], off
	global_load_dwordx4 v[14:17], v[18:19], off offset:1024
	global_load_dwordx4 v[0:3], v[18:19], off offset:3072
	global_load_dwordx4 v[4:7], v[18:19], off offset:2048
	s_load_dwordx2 s[4:5], s[0:1], 0x108
	s_ashr_i32 s3, s10, 11
	s_add_i32 s6, s70, 8
	s_cmp_lt_i32 s70, 0
	s_cselect_b32 s3, s3, s6
	s_mul_hi_i32 s6, s3, 0x9000
	s_mul_i32 s3, s3, 0x9000
	s_waitcnt lgkmcnt(0)
	s_add_u32 s3, s4, s3
	s_addc_u32 s7, s5, s6
	s_add_u32 s4, s3, 0x2906000
	s_addc_u32 s5, s7, 0
	s_add_u32 s6, s3, 0x2907000
	s_addc_u32 s7, s7, 0
	v_lshl_add_u64 v[18:19], s[6:7], 0, v[26:27]
	v_lshl_add_u64 v[30:31], s[12:13], 0, v[26:27]
	global_load_dwordx4 v[18:21], v[18:19], off
	v_lshl_add_u64 v[26:27], s[4:5], 0, v[26:27]
	global_load_dwordx4 v[22:25], v[30:31], off
	v_mov_b32_e32 v49, 0x358637bd
	global_load_dwordx4 v[26:29], v[26:27], off
	v_lshlrev_b64 v[34:35], 1, v[8:9]
	s_load_dwordx2 s[12:13], s[0:1], 0x108
	s_lshl_b64 s[10:11], s[10:11], 11
	s_mov_b32 s3, 0x3000000
	v_add_u32_e32 v32, 0x100, v8
	v_ashrrev_i32_e32 v33, 31, v32
	s_waitcnt lgkmcnt(0)
	s_add_u32 s12, s12, s10
	s_addc_u32 s13, s13, s11
	v_lshl_add_u64 v[36:37], s[12:13], 0, v[34:35]
	v_add_co_u32_e32 v36, vcc, s3, v36
	v_lshlrev_b64 v[32:33], 2, v[32:33]
	s_nop 0
	v_addc_co_u32_e32 v37, vcc, 0, v37, vcc
	s_waitcnt vmcnt(6)
	v_pk_mul_f32 v[38:39], v[12:13], v[12:13]
	v_pk_mul_f32 v[40:41], v[10:11], v[10:11]
	s_waitcnt vmcnt(5)
	v_pk_mul_f32 v[42:43], v[16:17], v[16:17]
	v_pk_mul_f32 v[44:45], v[14:15], v[14:15]
	v_pk_mov_b32 v[50:51], v[40:41], v[38:39] op_sel:[1,0]
	v_mov_b32_e32 v41, v39
	v_pk_mov_b32 v[38:39], v[44:45], v[42:43] op_sel:[1,0]
	v_mov_b32_e32 v45, v43
	s_waitcnt vmcnt(3)
	v_mul_f32_e32 v46, v5, v5
	v_mul_f32_e32 v48, v7, v7
	v_pk_add_f32 v[40:41], v[50:51], v[40:41]
	v_pk_add_f32 v[38:39], v[38:39], v[44:45]
	v_mul_f32_e32 v9, v0, v0
	v_mul_f32_e32 v52, v1, v1
	v_mul_f32_e32 v53, v2, v2
	v_mul_f32_e32 v54, v3, v3
	v_pk_fma_f32 v[42:43], v[4:5], v[4:5], v[46:47] op_sel_hi:[1,1,0]
	v_pk_fma_f32 v[46:47], v[6:7], v[6:7], v[48:49] op_sel_hi:[1,1,0]
	v_pk_add_f32 v[40:41], v[40:41], v[40:41] op_sel:[0,1] op_sel_hi:[1,0]
	v_pk_add_f32 v[38:39], v[38:39], v[38:39] op_sel:[0,1] op_sel_hi:[1,0]
	v_mov_b32_e32 v43, v53
	v_mov_b32_e32 v47, v54
	v_mov_b32_e32 v41, v9
	v_mov_b32_e32 v39, v52
	v_pk_add_f32 v[42:43], v[42:43], v[46:47]
	v_pk_add_f32 v[38:39], v[40:41], v[38:39]
	s_waitcnt vmcnt(2)
	v_pk_add_f32 v[20:21], v[20:21], 1.0 op_sel_hi:[1,0]
	v_pk_add_f32 v[38:39], v[38:39], v[42:43]
	v_pk_add_f32 v[18:19], v[18:19], 1.0 op_sel_hi:[1,0]
	v_add_f32_e32 v9, v38, v39
	s_nop 1
	v_add_f32_dpp v9, v9, v9 quad_perm:[1,0,3,2] row_mask:0xf bank_mask:0xf bound_ctrl:1
	s_nop 1
	v_add_f32_dpp v9, v9, v9 quad_perm:[2,3,0,1] row_mask:0xf bank_mask:0xf bound_ctrl:1
	s_nop 1
	v_add_f32_dpp v9, v9, v9 row_half_mirror row_mask:0xf bank_mask:0xf bound_ctrl:1
	s_nop 1
	v_add_f32_dpp v9, v9, v9 row_mirror row_mask:0xf bank_mask:0xf bound_ctrl:1
	s_nop 0
	v_readlane_b32 s14, v9, 16
	v_readlane_b32 s15, v9, 48
	v_readlane_b32 s12, v9, 0
	v_readlane_b32 s13, v9, 32
	v_mov_b32_e32 v38, s14
	v_mov_b32_e32 v39, s15
	v_pk_add_f32 v[38:39], s[12:13], v[38:39]
	s_nop 0
	v_add_f32_e32 v9, v38, v39
	v_fmac_f32_e32 v49, 0x3a800000, v9
	v_rsq_f32_e32 v38, v49
	s_nop 0
	v_pk_mul_f32 v[12:13], v[12:13], v[38:39] op_sel_hi:[1,0]
	v_pk_mul_f32 v[10:11], v[10:11], v[38:39] op_sel_hi:[1,0]
	s_waitcnt vmcnt(1)
; __device__ __forceinline__ unsigned pk2(float lo, float hi) { f32x2_t v = {lo, hi}; bf16x2_t b = __builtin_convertvector(v, bf16x2_t); return __builtin_bit_cast(unsigned, b); }
; __device__ __forceinline__ unsigned char* karg_ws() { return *(volatile KAS ucptr_t*)((const KAS char*)__builtin_amdgcn_kernarg_segment_ptr() + 264); }
; #define lane opq(lane_now())
; template <int MODE>
; __device__ __forceinline__ void sample_norm_rows(const float* gvec, int ish, int gw, int lane) {
;     ...
; #pragma unroll
;     for (int j = 0; j < 4; ++j) { const int col = 4 * (lane + 64 * j); const f32x4 g = *(const f32x4*)(gvec + col);
;         if (MODE == 0) { const f32x4 y = (v[j] * rstd * g) * (*(const f32x4*)(sh + D + col) + 1.f) + *(const f32x4*)(sh + col);
;             u32x2 o; o.x = pk2(y[0], y[1]); o.y = pk2(y[2], y[3]); *(u32x2*)((bf16*)(karg_ws() + WS_H) + (size_t)row * D + col) = o; }
;         else *(f32x4*)(X + col) = v[j] * rstd * g; }
	v_pk_mul_f32 v[12:13], v[24:25], v[12:13]
	v_pk_mul_f32 v[10:11], v[22:23], v[10:11]
	s_waitcnt vmcnt(0)
	v_pk_fma_f32 v[12:13], v[20:21], v[12:13], v[28:29]
	v_pk_fma_f32 v[10:11], v[18:19], v[10:11], v[26:27]
	v_lshl_add_u64 v[18:19], s[6:7], 0, v[32:33]
	v_cvt_pk_bf16_f32 v10, v10, v11
	v_cvt_pk_bf16_f32 v11, v12, v13
	global_store_dwordx2 v[36:37], v[10:11], off
	global_load_dwordx4 v[10:13], v[30:31], off offset:1024
	v_lshl_add_u64 v[22:23], s[4:5], 0, v[32:33]
	global_load_dwordx4 v[18:21], v[18:19], off
	v_pk_mul_f32 v[16:17], v[16:17], v[38:39] op_sel_hi:[1,0]
	global_load_dwordx4 v[22:25], v[22:23], off
	s_load_dwordx2 s[12:13], s[0:1], 0x108
	v_pk_mul_f32 v[14:15], v[14:15], v[38:39] op_sel_hi:[1,0]
	v_add_u32_e32 v26, 0x200, v8
	v_ashrrev_i32_e32 v27, 31, v26
	v_lshlrev_b64 v[26:27], 2, v[26:27]
	s_waitcnt lgkmcnt(0)
	s_add_u32 s12, s12, s10
	s_addc_u32 s13, s13, s11
	v_lshl_add_u64 v[28:29], s[12:13], 0, v[34:35]
	v_add_co_u32_e32 v28, vcc, s3, v28
	v_add_u32_e32 v8, 0x300, v8
	s_nop 0
	v_addc_co_u32_e32 v29, vcc, 0, v29, vcc
	v_ashrrev_i32_e32 v9, 31, v8
	v_pk_mul_f32 v[6:7], v[6:7], v[38:39] op_sel_hi:[1,0]
	v_pk_mul_f32 v[4:5], v[4:5], v[38:39] op_sel_hi:[1,0]
	v_pk_mul_f32 v[2:3], v[2:3], v[38:39] op_sel_hi:[1,0]
	v_pk_mul_f32 v[0:1], v[0:1], v[38:39] op_sel_hi:[1,0]
	s_waitcnt vmcnt(2)
	v_pk_mul_f32 v[10:11], v[10:11], v[14:15]
	v_pk_mul_f32 v[12:13], v[12:13], v[16:17]
	s_waitcnt vmcnt(1)
	v_pk_add_f32 v[14:15], v[20:21], 1.0 op_sel_hi:[1,0]
	v_pk_add_f32 v[16:17], v[18:19], 1.0 op_sel_hi:[1,0]
	s_waitcnt vmcnt(0)
	v_pk_fma_f32 v[12:13], v[14:15], v[12:13], v[24:25]
	v_pk_fma_f32 v[10:11], v[16:17], v[10:11], v[22:23]
	v_lshl_add_u64 v[14:15], s[6:7], 0, v[26:27]
	v_cvt_pk_bf16_f32 v10, v10, v11
	v_cvt_pk_bf16_f32 v11, v12, v13
	global_store_dwordx2 v[28:29], v[10:11], off offset:512
	global_load_dwordx4 v[10:13], v[30:31], off offset:2048
	v_lshl_add_u64 v[18:19], s[4:5], 0, v[26:27]
	global_load_dwordx4 v[14:17], v[14:15], off
	v_lshlrev_b64 v[22:23], 2, v[8:9]
	global_load_dwordx4 v[18:21], v[18:19], off
	s_load_dwordx2 s[12:13], s[0:1], 0x108
	s_waitcnt lgkmcnt(0)
	s_add_u32 s12, s12, s10
	s_addc_u32 s13, s13, s11
	v_lshl_add_u64 v[8:9], s[12:13], 0, v[34:35]
	v_add_co_u32_e32 v8, vcc, s3, v8
	s_waitcnt vmcnt(2)
	v_pk_mul_f32 v[4:5], v[4:5], v[10:11]
	v_pk_mul_f32 v[6:7], v[6:7], v[12:13]
	s_waitcnt vmcnt(1)
	v_pk_add_f32 v[10:11], v[16:17], 1.0 op_sel_hi:[1,0]
	v_pk_add_f32 v[12:13], v[14:15], 1.0 op_sel_hi:[1,0]
	s_waitcnt vmcnt(0)
	v_pk_fma_f32 v[6:7], v[6:7], v[10:11], v[20:21]
	v_pk_fma_f32 v[4:5], v[4:5], v[12:13], v[18:19]
	v_addc_co_u32_e32 v9, vcc, 0, v9, vcc
	v_cvt_pk_bf16_f32 v4, v4, v5
	v_cvt_pk_bf16_f32 v5, v6, v7
	global_store_dwordx2 v[8:9], v[4:5], off offset:1024
	v_lshl_add_u64 v[8:9], s[6:7], 0, v[22:23]
	global_load_dwordx4 v[4:7], v[30:31], off offset:3072
	v_lshl_add_u64 v[12:13], s[4:5], 0, v[22:23]
	global_load_dwordx4 v[8:11], v[8:9], off
	s_waitcnt vmcnt(1)
	v_pk_mul_f32 v[0:1], v[0:1], v[4:5]
	global_load_dwordx4 v[12:15], v[12:13], off
	s_load_dwordx2 s[4:5], s[0:1], 0x108
	v_pk_mul_f32 v[2:3], v[2:3], v[6:7]
	s_waitcnt vmcnt(1)
	v_pk_add_f32 v[4:5], v[10:11], 1.0 op_sel_hi:[1,0]
	v_pk_add_f32 v[6:7], v[8:9], 1.0 op_sel_hi:[1,0]
	s_waitcnt lgkmcnt(0)
	s_add_u32 s4, s4, s10
	s_addc_u32 s5, s5, s11
	v_lshl_add_u64 v[16:17], s[4:5], 0, v[34:35]
	v_add_co_u32_e32 v16, vcc, 0x3000000, v16
	s_waitcnt vmcnt(0)
	v_pk_fma_f32 v[2:3], v[2:3], v[4:5], v[14:15]
	v_pk_fma_f32 v[0:1], v[0:1], v[6:7], v[12:13]
	v_addc_co_u32_e32 v17, vcc, 0, v17, vcc
	v_cvt_pk_bf16_f32 v0, v0, v1
	v_cvt_pk_bf16_f32 v1, v2, v3
	global_store_dwordx2 v[16:17], v[0:1], off offset:1536

; __device__ __forceinline__ unsigned xb_ld(unsigned* p)              { return __hip_atomic_load(p, __ATOMIC_RELAXED, __HIP_MEMORY_SCOPE_AGENT); }
; __device__ __forceinline__ unsigned xb_add(unsigned* p, unsigned v) { return __hip_atomic_fetch_add(p, v, __ATOMIC_RELAXED, __HIP_MEMORY_SCOPE_AGENT); }
; #define XB_SPIN(cond, bar) do { unsigned _sp = 0; while (cond) { __builtin_amdgcn_s_sleep(1); \
;     if ((++_sp & 255u) == 0u) { if (xb_ld(&(bar)[XB_TMO])) break; if (_sp > XB_SPIN_CAP) { atomicAdd(&(bar)[XB_TMO], 1u); break; } } } } while (0)
; __device__ __forceinline__ void xcd_barrier(const XcdBarrier& b, bool leader) {
;     ...
;         const unsigned old = xb_add(&bar[XB_XSUB(b.x)], 1u);
;         const unsigned gen = old / nloc;
;         if (old + 1u == (gen + 1u) * nloc) {
;             __builtin_amdgcn_fence(__ATOMIC_RELEASE, "agent");
;             asm volatile("s_waitcnt vmcnt(0)" ::: "memory");
;             const unsigned og = xb_add(&bar[XB_TOP], 1u);
;             const unsigned tg = og / nx;
;             if (og + 1u == (tg + 1u) * nx) xb_add(&bar[XB_TOPGEN], 1u);
;             else XB_SPIN(xb_ld(&bar[XB_TOPGEN]) == tg, bar);
;             __builtin_amdgcn_fence(__ATOMIC_ACQUIRE, "agent");
;             xb_add(&bar[XB_XGEN(b.x)], 1u);
;             asm volatile("s_waitcnt vmcnt(0)" ::: "memory");
;         } else {
;             XB_SPIN(xb_ld(&bar[XB_XGEN(b.x)]) == gen, bar);
.LBB0_2150:
	s_or_b64 exec, exec, s[12:13]
	v_cvt_f32_u32_e32 v4, v2
	s_waitcnt vmcnt(0)
	v_readfirstlane_b32 s3, v3
	v_sub_u32_e32 v3, 0, v2
	v_rcp_iflag_f32_e32 v4, v4
	v_add_u32_e32 v5, s3, v1
	v_mul_f32_e32 v4, 0x4f7ffffe, v4
	v_cvt_u32_f32_e32 v4, v4
	v_mul_lo_u32 v1, v3, v4
	v_mul_hi_u32 v1, v4, v1
	v_add_u32_e32 v1, v4, v1
	v_mul_hi_u32 v1, v5, v1
	v_mul_lo_u32 v3, v1, v2
	v_sub_u32_e32 v3, v5, v3
	v_add_u32_e32 v4, 1, v1
	v_cmp_ge_u32_e32 vcc, v3, v2
	s_nop 1
	v_cndmask_b32_e32 v1, v1, v4, vcc
	v_sub_u32_e32 v4, v3, v2
	v_cndmask_b32_e32 v3, v3, v4, vcc
	v_add_u32_e32 v4, 1, v1
	v_cmp_ge_u32_e32 vcc, v3, v2
	v_add_u32_e32 v3, 1, v5
	s_nop 0
	v_cndmask_b32_e32 v1, v1, v4, vcc
	v_mul_lo_u32 v4, v2, v1
	v_add_u32_e32 v2, v4, v2
	v_cmp_ne_u32_e32 vcc, v3, v2
	s_and_saveexec_b64 s[10:11], vcc
	s_xor_b64 s[10:11], exec, s[10:11]
	s_cbranch_execz .LBB0_2164
	buffer_inv sc1
	s_waitcnt lgkmcnt(0)
	v_add_u32_e32 v1, 1, v1
	v_mul_lo_u32 v1, v1, v0
	v_mov_b32_e32 v0, 0x3000
	global_load_dword v0, v0, s[76:77] offset:1024 sc1
	s_add_u32 s14, s76, 0x3400
	s_addc_u32 s15, s77, 0
	s_waitcnt vmcnt(0)
	v_cmp_lt_u32_e32 vcc, v0, v1
	s_and_saveexec_b64 s[12:13], vcc
	s_cbranch_execz .LBB0_2163
	s_mov_b32 s3, 1
	s_mov_b64 s[16:17], 0
	v_mov_b32_e32 v239, v0
	v_mov_b32_e32 v0, 0
	s_branch .LBB0_2154

; __device__ __forceinline__ unsigned xb_ld(unsigned* p)              { return __hip_atomic_load(p, __ATOMIC_RELAXED, __HIP_MEMORY_SCOPE_AGENT); }
; #define XB_SPIN(cond, bar) do { unsigned _sp = 0; while (cond) { __builtin_amdgcn_s_sleep(1); \
;     if ((++_sp & 255u) == 0u) { if (xb_ld(&(bar)[XB_TMO])) break; if (_sp > XB_SPIN_CAP) { atomicAdd(&(bar)[XB_TMO], 1u); break; } } } } while (0)
; __device__ __forceinline__ void xcd_barrier(const XcdBarrier& b, bool leader) {
;     ...
;         } else {
;             XB_SPIN(xb_ld(&bar[XB_XGEN(b.x)]) == gen, bar);
.LBB0_2158:
	global_load_dword v239, v0, s[14:15] sc1
	s_add_i32 s3, s3, 1
	s_mov_b64 s[22:23], -1
	s_waitcnt vmcnt(1)
	v_cmp_ge_u32_e32 vcc, v239, v1
	s_orn2_b64 s[20:21], vcc, exec
	s_branch .LBB0_2153

; __device__ __forceinline__ unsigned xb_ld(unsigned* p)              { return __hip_atomic_load(p, __ATOMIC_RELAXED, __HIP_MEMORY_SCOPE_AGENT); }
; __device__ __forceinline__ unsigned xb_add(unsigned* p, unsigned v) { return __hip_atomic_fetch_add(p, v, __ATOMIC_RELAXED, __HIP_MEMORY_SCOPE_AGENT); }
; #define XB_SPIN(cond, bar) do { unsigned _sp = 0; while (cond) { __builtin_amdgcn_s_sleep(1); \
;     if ((++_sp & 255u) == 0u) { if (xb_ld(&(bar)[XB_TMO])) break; if (_sp > XB_SPIN_CAP) { atomicAdd(&(bar)[XB_TMO], 1u); break; } } } } while (0)
; __device__ __forceinline__ void xcd_barrier(const XcdBarrier& b, bool leader) {
;     ...
;         const unsigned old = xb_add(&bar[XB_XSUB(b.x)], 1u);
;         const unsigned gen = old / nloc;
;         if (old + 1u == (gen + 1u) * nloc) {
;             __builtin_amdgcn_fence(__ATOMIC_RELEASE, "agent");
;             asm volatile("s_waitcnt vmcnt(0)" ::: "memory");
;             const unsigned og = xb_add(&bar[XB_TOP], 1u);
;             const unsigned tg = og / nx;
;             if (og + 1u == (tg + 1u) * nx) xb_add(&bar[XB_TOPGEN], 1u);
;             else XB_SPIN(xb_ld(&bar[XB_TOPGEN]) == tg, bar);
;             __builtin_amdgcn_fence(__ATOMIC_ACQUIRE, "agent");
;             xb_add(&bar[XB_XGEN(b.x)], 1u);
;             asm volatile("s_waitcnt vmcnt(0)" ::: "memory");
;         } else {
;             XB_SPIN(xb_ld(&bar[XB_XGEN(b.x)]) == gen, bar);
;             __builtin_amdgcn_fence(__ATOMIC_ACQUIRE, "agent");
;             asm volatile("s_waitcnt vmcnt(0)" ::: "memory");
;         }
.LBB0_2163:
	s_or_b64 exec, exec, s[12:13]
.LBB0_2164:
	s_andn2_saveexec_b64 s[10:11], s[10:11]
	s_cbranch_execz .LBB0_2184
	s_mov_b64 s[10:11], exec
	buffer_wbl2 sc1
	s_waitcnt lgkmcnt(0)
	s_waitcnt vmcnt(0)
	v_mbcnt_lo_u32_b32 v1, s10, 0
	v_mbcnt_hi_u32_b32 v1, s11, v1
	v_cmp_eq_u32_e32 vcc, 0, v1
	s_and_saveexec_b64 s[12:13], vcc
	s_cbranch_execz .LBB0_2167
	s_bcnt1_i32_b64 s3, s[10:11]
	v_mov_b32_e32 v2, 0x3000
	v_mov_b32_e32 v3, s3
	global_atomic_add v2, v2, v3, s[76:77] offset:1024 sc0
.LBB0_2167:
	s_or_b64 exec, exec, s[12:13]
	buffer_inv sc1
	v_cvt_f32_u32_e32 v3, v0
	s_waitcnt vmcnt(0)
	v_readfirstlane_b32 s3, v2
	s_add_u32 s12, s76, 0x3500
	s_addc_u32 s13, s77, 0
	v_rcp_iflag_f32_e32 v3, v3
	v_add_u32_e32 v1, s3, v1
	v_add_u32_e32 v4, 1, v1
	s_mov_b64 s[14:15], -1
	v_mul_f32_e32 v2, 0x4f7ffffe, v3
	v_cvt_u32_f32_e32 v2, v2
	v_sub_u32_e32 v3, 0, v0
	v_mul_lo_u32 v3, v3, v2
	v_mul_hi_u32 v3, v2, v3
	v_add_u32_e32 v2, v2, v3
	v_mul_hi_u32 v2, v1, v2
	v_mul_lo_u32 v3, v2, v0
	v_sub_u32_e32 v1, v1, v3
	v_add_u32_e32 v5, 1, v2
	v_cmp_ge_u32_e32 vcc, v1, v0
	v_sub_u32_e32 v3, v1, v0
	s_nop 0
	v_cndmask_b32_e32 v2, v2, v5, vcc
	v_cndmask_b32_e32 v1, v1, v3, vcc
	v_add_u32_e32 v3, 1, v2
	v_cmp_ge_u32_e32 vcc, v1, v0
	s_nop 1
	v_cndmask_b32_e32 v2, v2, v3, vcc
	v_mul_lo_u32 v1, v0, v2
	v_add_u32_e32 v0, v1, v0
	v_mov_b32_e32 v2, v0
	v_cmp_ne_u32_e32 vcc, v4, v0
	v_mov_b64_e32 v[0:1], s[12:13]
	s_and_saveexec_b64 s[10:11], vcc
	s_cbranch_execz .LBB0_2179
	v_mov_b32_e32 v0, 0
	global_load_dword v1, v0, s[12:13] offset:-256 sc1
	s_mov_b64 s[18:19], 0
	s_waitcnt vmcnt(0)
	v_cmp_lt_u32_e32 vcc, v1, v2
	s_and_saveexec_b64 s[16:17], vcc
	s_cbranch_execz .LBB0_2178
	v_mov_b32_e32 v239, v1
	s_add_u32 s14, s76, 0x200
	s_addc_u32 s15, s77, 0
	s_mov_b32 s3, 1
	s_branch .LBB0_2171

; __device__ __forceinline__ unsigned xb_ld(unsigned* p)              { return __hip_atomic_load(p, __ATOMIC_RELAXED, __HIP_MEMORY_SCOPE_AGENT); }
; __device__ __forceinline__ unsigned xb_add(unsigned* p, unsigned v) { return __hip_atomic_fetch_add(p, v, __ATOMIC_RELAXED, __HIP_MEMORY_SCOPE_AGENT); }
; #define XB_SPIN(cond, bar) do { unsigned _sp = 0; while (cond) { __builtin_amdgcn_s_sleep(1); \
;     if ((++_sp & 255u) == 0u) { if (xb_ld(&(bar)[XB_TMO])) break; if (_sp > XB_SPIN_CAP) { atomicAdd(&(bar)[XB_TMO], 1u); break; } } } } while (0)
; __device__ __forceinline__ void xcd_barrier(const XcdBarrier& b, bool leader) {
;     ...
;             const unsigned og = xb_add(&bar[XB_TOP], 1u);
;             const unsigned tg = og / nx;
;             if (og + 1u == (tg + 1u) * nx) xb_add(&bar[XB_TOPGEN], 1u);
;             else XB_SPIN(xb_ld(&bar[XB_TOPGEN]) == tg, bar);
.LBB0_2175:
	global_load_dword v239, v0, s[12:13] offset:-256 sc1
	s_add_i32 s3, s3, 1
	s_mov_b64 s[22:23], -1
	s_waitcnt vmcnt(1)
	v_cmp_ge_u32_e32 vcc, v239, v2
	s_orn2_b64 s[26:27], vcc, exec
	s_branch .LBB0_2170

; __device__ __forceinline__ unsigned xb_ld(unsigned* p)              { return __hip_atomic_load(p, __ATOMIC_RELAXED, __HIP_MEMORY_SCOPE_AGENT); }
; __device__ __forceinline__ unsigned xb_add(unsigned* p, unsigned v) { return __hip_atomic_fetch_add(p, v, __ATOMIC_RELAXED, __HIP_MEMORY_SCOPE_AGENT); }
; #define XB_SPIN(cond, bar) do { unsigned _sp = 0; while (cond) { __builtin_amdgcn_s_sleep(1); \
;     if ((++_sp & 255u) == 0u) { if (xb_ld(&(bar)[XB_TMO])) break; if (_sp > XB_SPIN_CAP) { atomicAdd(&(bar)[XB_TMO], 1u); break; } } } } while (0)
; __device__ __forceinline__ void xcd_barrier(const XcdBarrier& b, bool leader) {
;     ...
;             xb_add(&bar[XB_XGEN(b.x)], 1u);
;             asm volatile("s_waitcnt vmcnt(0)" ::: "memory");
;         } else {
;             XB_SPIN(xb_ld(&bar[XB_XGEN(b.x)]) == gen, bar);
;             __builtin_amdgcn_fence(__ATOMIC_ACQUIRE, "agent");
;             asm volatile("s_waitcnt vmcnt(0)" ::: "memory");
;         }
;     }
;     __syncthreads();
; __global__ void __launch_bounds__(NTHR, 2) fwd_megakernel(Params P) {
;     ...
;     { pg8::Gemm g{H, (const bf16*)(ws + WS_WUP2), nullptr, nullptr, D}; pg8::StaticOrder S; S.init(MPAD, 2 * FF, G, wg);
;       EpiSwiglu E{ACT}; pg8::gemm_phase(lds, g, S, E, wave);
.LBB0_2181:
	s_or_b64 exec, exec, s[10:11]
	s_mov_b64 s[10:11], exec
	v_mbcnt_lo_u32_b32 v0, s10, 0
	v_mbcnt_hi_u32_b32 v0, s11, v0
	v_cmp_eq_u32_e32 vcc, 0, v0
	s_and_saveexec_b64 s[12:13], vcc
	s_cbranch_execz .LBB0_2183
	s_bcnt1_i32_b64 s3, s[10:11]
	v_mov_b32_e32 v0, 0x2000
	v_mov_b32_e32 v1, s3
.LBB0_2183:
	s_or_b64 exec, exec, s[12:13]
.LBB0_2184:
	s_or_b64 exec, exec, s[4:5]
	v_mov_b32_e32 v8, v166
	s_and_b64 vcc, exec, s[92:93]
	s_waitcnt lgkmcnt(0)
	s_barrier
	s_cbranch_vccnz .LBB0_2190
	s_ashr_i32 s3, s2, 31
	s_lshr_b32 s3, s3, 29
	s_add_i32 s3, s2, s3
	s_and_b32 s4, s3, -8
	s_sub_i32 s6, s2, s4
	s_cmp_gt_i32 s6, 5
	s_cbranch_scc0 .LBB0_2187
	s_mul_i32 s4, s6, 0xb2
	s_add_i32 s7, s4, 6
	s_cbranch_execz .LBB0_2188
	s_branch .LBB0_2189

; __device__ __forceinline__ unsigned xb_ld(unsigned* p)              { return __hip_atomic_load(p, __ATOMIC_RELAXED, __HIP_MEMORY_SCOPE_AGENT); }
; __device__ __forceinline__ unsigned xb_add(unsigned* p, unsigned v) { return __hip_atomic_fetch_add(p, v, __ATOMIC_RELAXED, __HIP_MEMORY_SCOPE_AGENT); }
; #define XB_SPIN(cond, bar) do { unsigned _sp = 0; while (cond) { __builtin_amdgcn_s_sleep(1); \
;     if ((++_sp & 255u) == 0u) { if (xb_ld(&(bar)[XB_TMO])) break; if (_sp > XB_SPIN_CAP) { atomicAdd(&(bar)[XB_TMO], 1u); break; } } } } while (0)
; __device__ __forceinline__ void xcd_barrier(const XcdBarrier& b, bool leader) {
;     ...
;         const unsigned old = xb_add(&bar[XB_XSUB(b.x)], 1u);
;         const unsigned gen = old / nloc;
;         if (old + 1u == (gen + 1u) * nloc) {
;             __builtin_amdgcn_fence(__ATOMIC_RELEASE, "agent");
;             asm volatile("s_waitcnt vmcnt(0)" ::: "memory");
;             const unsigned og = xb_add(&bar[XB_TOP], 1u);
;             const unsigned tg = og / nx;
;             if (og + 1u == (tg + 1u) * nx) xb_add(&bar[XB_TOPGEN], 1u);
;             else XB_SPIN(xb_ld(&bar[XB_TOPGEN]) == tg, bar);
;             __builtin_amdgcn_fence(__ATOMIC_ACQUIRE, "agent");
;             xb_add(&bar[XB_XGEN(b.x)], 1u);
;             asm volatile("s_waitcnt vmcnt(0)" ::: "memory");
;         } else {
;             XB_SPIN(xb_ld(&bar[XB_XGEN(b.x)]) == gen, bar);
;             __builtin_amdgcn_fence(__ATOMIC_ACQUIRE, "agent");
;             asm volatile("s_waitcnt vmcnt(0)" ::: "memory");
;         }
.LBB0_2279:
	s_or_b64 exec, exec, s[12:13]
.LBB0_2280:
	s_andn2_saveexec_b64 s[10:11], s[10:11]
	s_cbranch_execz .LBB0_2300
	s_mov_b64 s[10:11], exec
	buffer_wbl2 sc1
	s_waitcnt lgkmcnt(0)
	s_waitcnt vmcnt(0)
	v_mbcnt_lo_u32_b32 v1, s10, 0
	v_mbcnt_hi_u32_b32 v1, s11, v1
	v_cmp_eq_u32_e32 vcc, 0, v1
	s_and_saveexec_b64 s[12:13], vcc
	s_cbranch_execz .LBB0_2283
	s_bcnt1_i32_b64 s3, s[10:11]
	v_mov_b32_e32 v2, 0x3000
	v_mov_b32_e32 v3, s3
	global_atomic_add v2, v2, v3, s[76:77] offset:1024 sc0

; #define LAS __attribute__((address_space(3)))
;     __device__ bool next(int i, Unit& u) const { const bool ok = base.next(i >> 1, u); u.sub = i & 1; return ok; }
; __device__ __forceinline__ float* karg_out() { return *(volatile KAS fptr_t*)((const KAS char*)__builtin_amdgcn_kernarg_segment_ptr() + 256); }
; #define INP(k) karg_in(k)
;     __device__ bool next(int i, Unit& u) const {
;         const long L = (long)i * G + c; if (L >= nwg) return false;
;         int wgid = (int)L; { const int q = nwg / NXCD, r = nwg % NXCD, xcd = wgid % NXCD, off = wgid / NXCD; wgid = (xcd < r ? xcd * (q + 1) : r * (q + 1) + (xcd - r) * q) + off; }
;         const int nig = WGM * nN, gid = wgid / nig, fm = gid * WGM, gsz = (nM - fm) < WGM ? (nM - fm) : WGM;
;         u.pm = fm + ((wgid % nig) % gsz); u.pn = (wgid % nig) / gsz; u.sub = 0; return true;
; __global__ void __launch_bounds__(NTHR, 2) fwd_megakernel(Params P) {
;     ...
;     { pg8::Gemm g{ACT, (const bf16*)(ws + WS_WDN2), nullptr, nullptr, FF}; pg8::StaticOrder S; S.init(MPR, D, G, wg);
;       EpiResidNorm<1> E{karg_out(), nullptr, ADA + 8 * D, 0.5f, INP(31), nullptr, nullptr, (float*)(ws + WS_PART) + 131072, (unsigned*)(ws + WS_CNT) + 128, (LAS float*)(lds + 131072)}; pg8::gemm_phase(lds, g, S, E, wave);
.LBB0_2299:
	s_or_b64 exec, exec, s[12:13]
.LBB0_2300:
	s_or_b64 exec, exec, s[4:5]
	s_waitcnt lgkmcnt(0)
	s_barrier
	s_load_dwordx2 s[14:15], s[0:1], 0x100
	s_load_dwordx2 s[16:17], s[0:1], 0xf8
	v_mov_b32_e32 v8, v166
	s_and_b64 vcc, exec, s[90:91]
	s_cbranch_vccnz .LBB0_2306
	s_ashr_i32 s3, s2, 31
	s_lshr_b32 s3, s3, 29
	s_add_i32 s7, s2, s3
	s_and_b32 s3, s7, -8
	s_sub_i32 s3, s2, s3
	s_cmp_gt_i32 s3, -1
	s_cbranch_scc0 .LBB0_2303
	s_lshl_b32 s6, s3, 5
	s_ashr_i32 s4, s7, 3
	s_cbranch_execz .LBB0_2304
	s_branch .LBB0_2305

; __device__ __forceinline__ unsigned xb_ld(unsigned* p)              { return __hip_atomic_load(p, __ATOMIC_RELAXED, __HIP_MEMORY_SCOPE_AGENT); }
; __device__ __forceinline__ unsigned xb_add(unsigned* p, unsigned v) { return __hip_atomic_fetch_add(p, v, __ATOMIC_RELAXED, __HIP_MEMORY_SCOPE_AGENT); }
; #define XB_SPIN(cond, bar) do { unsigned _sp = 0; while (cond) { __builtin_amdgcn_s_sleep(1); \
;     if ((++_sp & 255u) == 0u) { if (xb_ld(&(bar)[XB_TMO])) break; if (_sp > XB_SPIN_CAP) { atomicAdd(&(bar)[XB_TMO], 1u); break; } } } } while (0)
; __device__ __forceinline__ void xcd_barrier(const XcdBarrier& b, bool leader) {
;     ...
;         const unsigned old = xb_add(&bar[XB_XSUB(b.x)], 1u);
;         const unsigned gen = old / nloc;
;         if (old + 1u == (gen + 1u) * nloc) {
;             __builtin_amdgcn_fence(__ATOMIC_RELEASE, "agent");
;             asm volatile("s_waitcnt vmcnt(0)" ::: "memory");
;             const unsigned og = xb_add(&bar[XB_TOP], 1u);
;             const unsigned tg = og / nx;
;             if (og + 1u == (tg + 1u) * nx) xb_add(&bar[XB_TOPGEN], 1u);
;             else XB_SPIN(xb_ld(&bar[XB_TOPGEN]) == tg, bar);
;             __builtin_amdgcn_fence(__ATOMIC_ACQUIRE, "agent");
;             xb_add(&bar[XB_XGEN(b.x)], 1u);
;             asm volatile("s_waitcnt vmcnt(0)" ::: "memory");
;         } else {
;             XB_SPIN(xb_ld(&bar[XB_XGEN(b.x)]) == gen, bar);
.LBB0_2386:
	s_or_b64 exec, exec, s[10:11]
	v_cvt_f32_u32_e32 v4, v2
	s_waitcnt vmcnt(0)
	v_readfirstlane_b32 s6, v3
	v_sub_u32_e32 v3, 0, v2
	v_rcp_iflag_f32_e32 v4, v4
	v_add_u32_e32 v5, s6, v1
	v_mul_f32_e32 v4, 0x4f7ffffe, v4
	v_cvt_u32_f32_e32 v4, v4
	v_mul_lo_u32 v1, v3, v4
	v_mul_hi_u32 v1, v4, v1
	v_add_u32_e32 v1, v4, v1
	v_mul_hi_u32 v1, v5, v1
	v_mul_lo_u32 v3, v1, v2
	v_sub_u32_e32 v3, v5, v3
	v_add_u32_e32 v4, 1, v1
	v_cmp_ge_u32_e32 vcc, v3, v2
	s_nop 1
	v_cndmask_b32_e32 v1, v1, v4, vcc
	v_sub_u32_e32 v4, v3, v2
	v_cndmask_b32_e32 v3, v3, v4, vcc
	v_add_u32_e32 v4, 1, v1
	v_cmp_ge_u32_e32 vcc, v3, v2
	v_add_u32_e32 v3, 1, v5
	s_nop 0
	v_cndmask_b32_e32 v1, v1, v4, vcc
	v_mul_lo_u32 v4, v2, v1
	v_add_u32_e32 v2, v4, v2
	v_cmp_ne_u32_e32 vcc, v3, v2
	s_and_saveexec_b64 s[6:7], vcc
	s_xor_b64 s[6:7], exec, s[6:7]
	s_cbranch_execz .LBB0_2400
	buffer_inv sc1
	s_waitcnt lgkmcnt(0)
	v_add_u32_e32 v1, 1, v1
	v_mul_lo_u32 v1, v1, v0
	v_mov_b32_e32 v0, 0x3000
	global_load_dword v0, v0, s[76:77] offset:1024 sc1
	s_add_u32 s12, s76, 0x3400
	s_addc_u32 s13, s77, 0
	s_waitcnt vmcnt(0)
	v_cmp_lt_u32_e32 vcc, v0, v1
	s_and_saveexec_b64 s[10:11], vcc
	s_cbranch_execz .LBB0_2399
	s_mov_b32 s24, 1
	s_mov_b64 s[14:15], 0
	v_mov_b32_e32 v239, v0
	v_mov_b32_e32 v0, 0
	s_branch .LBB0_2390

; __device__ __forceinline__ unsigned xb_ld(unsigned* p)              { return __hip_atomic_load(p, __ATOMIC_RELAXED, __HIP_MEMORY_SCOPE_AGENT); }
; __device__ __forceinline__ unsigned xb_add(unsigned* p, unsigned v) { return __hip_atomic_fetch_add(p, v, __ATOMIC_RELAXED, __HIP_MEMORY_SCOPE_AGENT); }
; #define XB_SPIN(cond, bar) do { unsigned _sp = 0; while (cond) { __builtin_amdgcn_s_sleep(1); \
;     if ((++_sp & 255u) == 0u) { if (xb_ld(&(bar)[XB_TMO])) break; if (_sp > XB_SPIN_CAP) { atomicAdd(&(bar)[XB_TMO], 1u); break; } } } } while (0)
; __device__ __forceinline__ void xcd_barrier(const XcdBarrier& b, bool leader) {
;     ...
;         const unsigned old = xb_add(&bar[XB_XSUB(b.x)], 1u);
;         const unsigned gen = old / nloc;
;         if (old + 1u == (gen + 1u) * nloc) {
;             __builtin_amdgcn_fence(__ATOMIC_RELEASE, "agent");
;             asm volatile("s_waitcnt vmcnt(0)" ::: "memory");
;             const unsigned og = xb_add(&bar[XB_TOP], 1u);
;             const unsigned tg = og / nx;
;             if (og + 1u == (tg + 1u) * nx) xb_add(&bar[XB_TOPGEN], 1u);
;             else XB_SPIN(xb_ld(&bar[XB_TOPGEN]) == tg, bar);
;             __builtin_amdgcn_fence(__ATOMIC_ACQUIRE, "agent");
;             xb_add(&bar[XB_XGEN(b.x)], 1u);
;             asm volatile("s_waitcnt vmcnt(0)" ::: "memory");
;         } else {
;             XB_SPIN(xb_ld(&bar[XB_XGEN(b.x)]) == gen, bar);
;             __builtin_amdgcn_fence(__ATOMIC_ACQUIRE, "agent");
;             asm volatile("s_waitcnt vmcnt(0)" ::: "memory");
;         }
.LBB0_2399:
	s_or_b64 exec, exec, s[10:11]
.LBB0_2400:
	s_andn2_saveexec_b64 s[6:7], s[6:7]
	s_cbranch_execz .LBB0_2420
	s_mov_b64 s[6:7], exec
	buffer_wbl2 sc1
	s_waitcnt lgkmcnt(0)
	s_waitcnt vmcnt(0)
	v_mbcnt_lo_u32_b32 v1, s6, 0
	v_mbcnt_hi_u32_b32 v1, s7, v1
	v_cmp_eq_u32_e32 vcc, 0, v1
	s_and_saveexec_b64 s[10:11], vcc
	s_cbranch_execz .LBB0_2403
	s_bcnt1_i32_b64 s6, s[6:7]
	v_mov_b32_e32 v2, 0x3000
	v_mov_b32_e32 v3, s6
	global_atomic_add v2, v2, v3, s[76:77] offset:1024 sc0
.LBB0_2403:
	s_or_b64 exec, exec, s[10:11]
	buffer_inv sc1
	v_cvt_f32_u32_e32 v3, v0
	s_waitcnt vmcnt(0)
	v_readfirstlane_b32 s6, v2
	s_add_u32 s10, s76, 0x3500
	s_addc_u32 s11, s77, 0
	v_rcp_iflag_f32_e32 v3, v3
	v_add_u32_e32 v1, s6, v1
	v_add_u32_e32 v4, 1, v1
	s_mov_b64 s[12:13], -1
	v_mul_f32_e32 v2, 0x4f7ffffe, v3
	v_cvt_u32_f32_e32 v2, v2
	v_sub_u32_e32 v3, 0, v0
	v_mul_lo_u32 v3, v3, v2
	v_mul_hi_u32 v3, v2, v3
	v_add_u32_e32 v2, v2, v3
	v_mul_hi_u32 v2, v1, v2
	v_mul_lo_u32 v3, v2, v0
	v_sub_u32_e32 v1, v1, v3
	v_add_u32_e32 v5, 1, v2
	v_cmp_ge_u32_e32 vcc, v1, v0
	v_sub_u32_e32 v3, v1, v0
	s_nop 0
	v_cndmask_b32_e32 v2, v2, v5, vcc
	v_cndmask_b32_e32 v1, v1, v3, vcc
	v_add_u32_e32 v3, 1, v2
	v_cmp_ge_u32_e32 vcc, v1, v0
	s_nop 1
	v_cndmask_b32_e32 v2, v2, v3, vcc
	v_mul_lo_u32 v1, v0, v2
	v_add_u32_e32 v0, v1, v0
	v_mov_b32_e32 v2, v0
	v_cmp_ne_u32_e32 vcc, v4, v0
	v_mov_b64_e32 v[0:1], s[10:11]
	s_and_saveexec_b64 s[6:7], vcc
	s_cbranch_execz .LBB0_2415
	v_mov_b32_e32 v0, 0
	global_load_dword v1, v0, s[10:11] offset:-256 sc1
	s_mov_b64 s[16:17], 0
	s_waitcnt vmcnt(0)
	v_cmp_lt_u32_e32 vcc, v1, v2
	s_and_saveexec_b64 s[14:15], vcc
	s_cbranch_execz .LBB0_2414
	v_mov_b32_e32 v239, v1
	s_add_u32 s12, s76, 0x200
	s_addc_u32 s13, s77, 0
	s_mov_b32 s26, 1
	s_branch .LBB0_2407

; __device__ __forceinline__ unsigned pk2(float lo, float hi) { f32x2_t v = {lo, hi}; bf16x2_t b = __builtin_convertvector(v, bf16x2_t); return __builtin_bit_cast(unsigned, b); }
; __device__ __forceinline__ float rsq_f(float x) { return __builtin_amdgcn_rsqf(x); }
; __device__ __forceinline__ float* karg_out() { return *(volatile KAS fptr_t*)((const KAS char*)__builtin_amdgcn_kernarg_segment_ptr() + 256); }
; __device__ __forceinline__ unsigned char* karg_ws() { return *(volatile KAS ucptr_t*)((const KAS char*)__builtin_amdgcn_kernarg_segment_ptr() + 264); }
; __device__ __forceinline__ unsigned xb_ld(unsigned* p)              { return __hip_atomic_load(p, __ATOMIC_RELAXED, __HIP_MEMORY_SCOPE_AGENT); }
; __device__ __forceinline__ unsigned xb_add(unsigned* p, unsigned v) { return __hip_atomic_fetch_add(p, v, __ATOMIC_RELAXED, __HIP_MEMORY_SCOPE_AGENT); }
; template <int MODE>
; __device__ __forceinline__ void sample_norm_rows(const float* gvec, int ish, int gw, int lane) {
;     if (gw >= NS) return;
;     const int row = MPR + gw; float* X = karg_out() + (size_t)row * D;
;     f32x4 v[4]; float s = 0.f;
; #pragma unroll
;     for (int j = 0; j < 4; ++j) { v[j] = *(const f32x4*)(X + 4 * (lane + 64 * j)); s += (v[j][0] * v[j][0] + v[j][1] * v[j][1]) + (v[j][2] * v[j][2] + v[j][3] * v[j][3]); }
;     const float rstd = rsq_f(wave_sum(s) * (1.f / D) + EPS);
;     const float* sh = (const float*)(karg_ws() + WS_ADA) + (size_t)cond_of_row(row) * NADA + ish * D;
; #pragma unroll
;     for (int j = 0; j < 4; ++j) { const int col = 4 * (lane + 64 * j); const f32x4 g = *(const f32x4*)(gvec + col);
;         if (MODE == 0) { const f32x4 y = (v[j] * rstd * g) * (*(const f32x4*)(sh + D + col) + 1.f) + *(const f32x4*)(sh + col);
;             u32x2 o; o.x = pk2(y[0], y[1]); o.y = pk2(y[2], y[3]); *(u32x2*)((bf16*)(karg_ws() + WS_H) + (size_t)row * D + col) = o; }
;         else *(f32x4*)(X + col) = v[j] * rstd * g; }
; __device__ __forceinline__ void xcd_barrier(const XcdBarrier& b, bool leader) {
;     ...
;             xb_add(&bar[XB_XGEN(b.x)], 1u);
;             asm volatile("s_waitcnt vmcnt(0)" ::: "memory");
;         } else {
;             XB_SPIN(xb_ld(&bar[XB_XGEN(b.x)]) == gen, bar);
;             __builtin_amdgcn_fence(__ATOMIC_ACQUIRE, "agent");
;             asm volatile("s_waitcnt vmcnt(0)" ::: "memory");
;         }
;     }
;     __syncthreads();
.LBB0_2417:
	s_or_b64 exec, exec, s[6:7]
	s_mov_b64 s[6:7], exec
	v_mbcnt_lo_u32_b32 v0, s6, 0
	v_mbcnt_hi_u32_b32 v0, s7, v0
	v_cmp_eq_u32_e32 vcc, 0, v0
	s_and_saveexec_b64 s[10:11], vcc
	s_cbranch_execz .LBB0_2419
	s_bcnt1_i32_b64 s6, s[6:7]
	v_mov_b32_e32 v0, 0x2000
	v_mov_b32_e32 v1, s6
.LBB0_2419:
	s_or_b64 exec, exec, s[10:11]
.LBB0_2420:
	s_or_b64 exec, exec, s[2:3]
	s_waitcnt lgkmcnt(0)
	s_barrier
	s_load_dwordx2 s[2:3], s[0:1], 0xf8
	s_and_b64 vcc, exec, s[8:9]
	s_cbranch_vccnz .LBB0_2422
	s_load_dwordx2 s[4:5], s[0:1], 0x100
	s_ashr_i32 s71, s70, 31
	v_lshlrev_b32_e32 v0, 2, v166
	s_lshl_b64 s[6:7], s[70:71], 12
	v_ashrrev_i32_e32 v1, 31, v0
	s_waitcnt lgkmcnt(0)
	s_add_u32 s4, s4, s6
	s_addc_u32 s5, s5, s7
	v_lshlrev_b64 v[16:17], 2, v[0:1]
	v_lshl_add_u64 v[8:9], s[4:5], 0, v[16:17]
	s_mov_b64 s[4:5], 0x4000000
	v_lshl_add_u64 v[20:21], v[8:9], 0, s[4:5]
	v_add_co_u32_e32 v22, vcc, 0x4000000, v8
	global_load_dwordx4 v[0:3], v[20:21], off offset:1024
	global_load_dwordx4 v[4:7], v[20:21], off offset:2048
	v_addc_co_u32_e32 v23, vcc, 0, v9, vcc
	global_load_dwordx4 v[8:11], v[22:23], off
	global_load_dwordx4 v[12:15], v[20:21], off offset:3072
	v_lshl_add_u64 v[24:25], s[2:3], 0, v[16:17]
	s_load_dwordx2 s[0:1], s[0:1], 0x108
	global_load_dwordx4 v[16:19], v[24:25], off
	v_mov_b32_e32 v40, 0x358637bd
	s_waitcnt vmcnt(4)
	v_pk_mul_f32 v[26:27], v[2:3], v[2:3]
	v_pk_mul_f32 v[28:29], v[0:1], v[0:1]
	s_waitcnt vmcnt(3)
	v_mul_f32_e32 v30, v5, v5
	v_mul_f32_e32 v32, v7, v7
	s_waitcnt vmcnt(2)
	v_pk_mul_f32 v[34:35], v[10:11], v[10:11]
	v_pk_mul_f32 v[36:37], v[8:9], v[8:9]
	v_pk_mov_b32 v[38:39], v[28:29], v[26:27] op_sel:[1,0]
	v_mov_b32_e32 v29, v27
	s_waitcnt vmcnt(1)
	v_mul_f32_e32 v43, v14, v14
	v_mul_f32_e32 v44, v15, v15
	v_pk_fma_f32 v[26:27], v[4:5], v[4:5], v[30:31] op_sel_hi:[1,1,0]
	v_pk_fma_f32 v[30:31], v[6:7], v[6:7], v[32:33] op_sel_hi:[1,1,0]
	v_pk_mov_b32 v[32:33], v[36:37], v[34:35] op_sel:[1,0]
	v_mov_b32_e32 v37, v35
	v_pk_add_f32 v[28:29], v[38:39], v[28:29]
	v_mov_b32_e32 v27, v43
	v_mov_b32_e32 v31, v44
	v_pk_add_f32 v[32:33], v[32:33], v[36:37]
	v_mul_f32_e32 v41, v12, v12
	v_mul_f32_e32 v42, v13, v13
	v_pk_add_f32 v[28:29], v[28:29], v[28:29] op_sel:[0,1] op_sel_hi:[1,0]
	v_pk_add_f32 v[26:27], v[26:27], v[30:31]
	v_pk_add_f32 v[30:31], v[32:33], v[32:33] op_sel:[0,1] op_sel_hi:[1,0]
	v_mov_b32_e32 v29, v42
	v_mov_b32_e32 v31, v41
	v_pk_add_f32 v[28:29], v[30:31], v[28:29]
	s_nop 0
	v_pk_add_f32 v[26:27], v[28:29], v[26:27]
	s_nop 0
	v_add_f32_e32 v26, v26, v27
	s_nop 1
	v_add_f32_dpp v26, v26, v26 quad_perm:[1,0,3,2] row_mask:0xf bank_mask:0xf bound_ctrl:1
	s_nop 1
	v_add_f32_dpp v26, v26, v26 quad_perm:[2,3,0,1] row_mask:0xf bank_mask:0xf bound_ctrl:1
	s_nop 1
	v_add_f32_dpp v26, v26, v26 row_half_mirror row_mask:0xf bank_mask:0xf bound_ctrl:1
	s_nop 1
	v_add_f32_dpp v26, v26, v26 row_mirror row_mask:0xf bank_mask:0xf bound_ctrl:1
	s_nop 0
	v_readlane_b32 s2, v26, 16
	v_readlane_b32 s3, v26, 48
	s_waitcnt lgkmcnt(0)
	v_readlane_b32 s0, v26, 0
	v_readlane_b32 s1, v26, 32
	v_mov_b32_e32 v26, s2
	v_mov_b32_e32 v27, s3
	v_pk_add_f32 v[26:27], s[0:1], v[26:27]
	s_nop 0
	v_add_f32_e32 v26, v26, v27
	v_fmac_f32_e32 v40, 0x3a800000, v26
	v_rsq_f32_e32 v26, v40
	s_nop 0
	v_pk_mul_f32 v[8:9], v[8:9], v[26:27] op_sel_hi:[1,0]
	v_pk_mul_f32 v[10:11], v[10:11], v[26:27] op_sel_hi:[1,0]
	s_waitcnt vmcnt(0)
	v_pk_mul_f32 v[8:9], v[16:17], v[8:9]
	v_pk_mul_f32 v[10:11], v[18:19], v[10:11]
	global_store_dwordx4 v[22:23], v[8:11], off
	global_load_dwordx4 v[8:11], v[24:25], off offset:1024
	v_pk_mul_f32 v[2:3], v[2:3], v[26:27] op_sel_hi:[1,0]
	v_pk_mul_f32 v[0:1], v[0:1], v[26:27] op_sel_hi:[1,0]
	v_pk_mul_f32 v[6:7], v[6:7], v[26:27] op_sel_hi:[1,0]
	v_pk_mul_f32 v[4:5], v[4:5], v[26:27] op_sel_hi:[1,0]
	s_waitcnt vmcnt(0)
	v_pk_mul_f32 v[0:1], v[8:9], v[0:1]
	v_pk_mul_f32 v[2:3], v[10:11], v[2:3]
	global_store_dwordx4 v[20:21], v[0:3], off offset:1024
	global_load_dwordx4 v[0:3], v[24:25], off offset:2048
	s_waitcnt vmcnt(0)
	v_pk_mul_f32 v[0:1], v[0:1], v[4:5]
	v_pk_mul_f32 v[2:3], v[2:3], v[6:7]
	global_store_dwordx4 v[20:21], v[0:3], off offset:2048
	global_load_dwordx4 v[0:3], v[24:25], off offset:3072
	v_pk_mul_f32 v[4:5], v[14:15], v[26:27] op_sel_hi:[1,0]
	v_pk_mul_f32 v[6:7], v[12:13], v[26:27] op_sel_hi:[1,0]
	s_waitcnt vmcnt(0)
	v_pk_mul_f32 v[2:3], v[2:3], v[4:5]
	v_pk_mul_f32 v[0:1], v[0:1], v[6:7]
	global_store_dwordx4 v[20:21], v[0:3], off offset:3072
